# RWKV ring poll: progress counters read early (step 13), fast-path test at block start
# baseline (speedup 1.0000x reference)
; DEVINL u16 f2bf(float a) { return (u16)(pk2(a, 0.f) & 0xffffu); }
; #define RW_STEP2(B) RW_STEP(B, WvA, XA, KrA, vhA, WvB, XB, KrB, vhB); RW_STEP((B) + 1, WvB, XB, KrB, vhB, WvA, XA, KrA, vhA)
; #define RW_STEP4(B) RW_STEP2(B); RW_STEP2((B) + 2)
; template <int DIR>
; DEVINL void rwkv_scan_dir(const Params& p, int task, int lane, int wave) {
;     ...
; #pragma unroll 1
;   for (int st = 0; st < 4096; st += 32) {
;     RW_STEP(0, WvA, XA, KrA, vhA, WvB, XB, KrB, vhB);
;     if (st > 0) { const int q0 = st - 16 + seg; yo[(long)(DIR ? (4095 - q0) : q0) * 1024] = f2bf(ykeep); }
;     RW_STEP(1, WvB, XB, KrB, vhB, WvA, XA, KrA, vhA);
;     RW_STEP2(2); RW_STEP4(4); RW_STEP4(8); RW_STEP4(12);
;     RW_STEP(16, WvA, XA, KrA, vhA, WvB, XB, KrB, vhB);
;     { const int q0 = st + seg; yo[(long)(DIR ? (4095 - q0) : q0) * 1024] = f2bf(ykeep); }
;     RW_STEP(17, WvB, XB, KrB, vhB, WvA, XA, KrA, vhA);
;     RW_STEP2(18); RW_STEP4(20); RW_STEP4(24); RW_STEP4(28);
;   }
.Lrw_test_d0p:
	v_min3_u32 v100, v100, v101, v102
	v_min3_u32 v104, v104, v105, v106
	v_min_u32_e32 v100, v100, v103
	v_min_u32_e32 v104, v104, v107
	s_nop 0
	v_readfirstlane_b32 s24, v100
	v_readfirstlane_b32 s26, v104
	s_nop 3
	s_cmp_lt_u32 s24, s43
	s_cbranch_scc1 .Lrw_again_d0p
	s_cmp_ge_u32 s26, s44
	s_cbranch_scc1 .Lrw_ready_d0p

; DEVINL u16 f2bf(float a) { return (u16)(pk2(a, 0.f) & 0xffffu); }
; #define RW_STEP2(B) RW_STEP(B, WvA, XA, KrA, vhA, WvB, XB, KrB, vhB); RW_STEP((B) + 1, WvB, XB, KrB, vhB, WvA, XA, KrA, vhA)
; #define RW_STEP4(B) RW_STEP2(B); RW_STEP2((B) + 2)
; template <int DIR>
; DEVINL void rwkv_scan_dir(const Params& p, int task, int lane, int wave) {
;     ...
; #pragma unroll 1
;   for (int st = 0; st < 4096; st += 32) {
;     RW_STEP(0, WvA, XA, KrA, vhA, WvB, XB, KrB, vhB);
;     if (st > 0) { const int q0 = st - 16 + seg; yo[(long)(DIR ? (4095 - q0) : q0) * 1024] = f2bf(ykeep); }
;     RW_STEP(1, WvB, XB, KrB, vhB, WvA, XA, KrA, vhA);
;     RW_STEP2(2); RW_STEP4(4); RW_STEP4(8); RW_STEP4(12);
;     RW_STEP(16, WvA, XA, KrA, vhA, WvB, XB, KrB, vhB);
;     { const int q0 = st + seg; yo[(long)(DIR ? (4095 - q0) : q0) * 1024] = f2bf(ykeep); }
;     RW_STEP(17, WvB, XB, KrB, vhB, WvA, XA, KrA, vhA);
;     RW_STEP2(18); RW_STEP4(20); RW_STEP4(24); RW_STEP4(28);
;   }
.Lrw_nofull_d0:
	s_waitcnt vmcnt(1)
	s_add_u32 s3, s15, 3
	v_mov_b32_e32 v69, s3
	ds_write_b32 v23, v69
	s_add_u32 s43, s15, 2
	s_sub_u32 s44, s15, 4
	s_max_i32 s44, s44, 0
	s_mov_b32 s42, 0
	s_branch .Lrw_test_d0

.Lrw_skip_d0:
	ds_read_b64 v[84:85], v6 offset:3088
	ds_read_b128 v[86:89], v6 offset:3344
	ds_read_b128 v[90:93], v6 offset:3600
	ds_read_u16 v94, v7 offset:3088
	v_fma_mix_f32 v14, v10, v38, 0 op_sel:[0,0,0] op_sel_hi:[0,1,0]
	v_fma_mix_f32 v48, v10, v32, 0 op_sel:[0,0,0] op_sel_hi:[0,1,0]
	v_fma_mix_f32 v14, v11, v38, v14 op_sel:[0,1,0] op_sel_hi:[0,1,0]
	v_fma_mix_f32 v48, v11, v32, v48 op_sel:[0,1,0] op_sel_hi:[0,1,0]
	v_fma_mix_f32 v14, v12, v39, v14 op_sel:[0,0,0] op_sel_hi:[0,1,0]
	v_fma_mix_f32 v48, v12, v33, v48 op_sel:[0,0,0] op_sel_hi:[0,1,0]
	v_fma_mix_f32 v14, v13, v39, v14 op_sel:[0,1,0] op_sel_hi:[0,1,0]
	v_fma_mix_f32 v16, v10, v36, 0 op_sel:[0,0,0] op_sel_hi:[0,1,0]
	v_fma_mix_f32 v17, v11, v36, 0 op_sel:[0,1,0] op_sel_hi:[0,1,0]
	v_add_f32_dpp v20, v14, v14 quad_perm:[1,0,3,2] row_mask:0xf bank_mask:0xf bound_ctrl:1
	v_fma_mix_f32 v48, v13, v33, v48 op_sel:[0,1,0] op_sel_hi:[0,1,0]
	v_fma_mix_f32 v18, v12, v37, 0 op_sel:[0,0,0] op_sel_hi:[0,1,0]
	v_add_f32_dpp v20, v20, v20 quad_perm:[2,3,0,1] row_mask:0xf bank_mask:0xf bound_ctrl:1
	v_fma_mix_f32 v19, v13, v37, 0 op_sel:[0,1,0] op_sel_hi:[0,1,0]
	v_fma_mix_f32 v16, v46, v42, v16 op_sel:[0,0,0] op_sel_hi:[1,1,0]
	v_add_f32_dpp v20, v20, v20 row_half_mirror row_mask:0xf bank_mask:0xf bound_ctrl:1
	v_fma_mix_f32 v17, v46, v42, v17 op_sel:[0,1,0] op_sel_hi:[1,1,0]
	v_fma_mix_f32 v18, v46, v43, v18 op_sel:[0,0,0] op_sel_hi:[1,1,0]
	v_add_f32_dpp v20, v20, v20 row_mirror row_mask:0xf bank_mask:0xf bound_ctrl:1
	v_fma_mix_f32 v19, v46, v43, v19 op_sel:[0,1,0] op_sel_hi:[1,1,0]
	v_fma_mix_f32 v10, v20, v40, v16 op_sel:[0,0,0] op_sel_hi:[0,1,0]
	v_fma_mix_f32 v11, v20, v40, v17 op_sel:[0,1,0] op_sel_hi:[0,1,0]
	v_fma_mix_f32 v12, v20, v41, v18 op_sel:[0,0,0] op_sel_hi:[0,1,0]
	v_fma_mix_f32 v13, v20, v41, v19 op_sel:[0,1,0] op_sel_hi:[0,1,0]
	s_waitcnt lgkmcnt(4)
	ds_read_b64 v[24:25], v6 offset:4112
	ds_read_b128 v[26:29], v6 offset:4368
	ds_read_b128 v[30:33], v6 offset:4624
	ds_read_u16 v34, v7 offset:4112
	v_fma_mix_f32 v14, v10, v74, 0 op_sel:[0,0,0] op_sel_hi:[0,1,0]
	v_fma_mix_f32 v49, v10, v44, 0 op_sel:[0,0,0] op_sel_hi:[0,1,0]
	v_fma_mix_f32 v14, v11, v74, v14 op_sel:[0,1,0] op_sel_hi:[0,1,0]
	v_fma_mix_f32 v49, v11, v44, v49 op_sel:[0,1,0] op_sel_hi:[0,1,0]
	v_fma_mix_f32 v14, v12, v75, v14 op_sel:[0,0,0] op_sel_hi:[0,1,0]
	v_fma_mix_f32 v49, v12, v45, v49 op_sel:[0,0,0] op_sel_hi:[0,1,0]
	v_fma_mix_f32 v14, v13, v75, v14 op_sel:[0,1,0] op_sel_hi:[0,1,0]
	v_fma_mix_f32 v16, v10, v72, 0 op_sel:[0,0,0] op_sel_hi:[0,1,0]
	v_fma_mix_f32 v17, v11, v72, 0 op_sel:[0,1,0] op_sel_hi:[0,1,0]
	v_add_f32_dpp v20, v14, v14 quad_perm:[1,0,3,2] row_mask:0xf bank_mask:0xf bound_ctrl:1
	v_fma_mix_f32 v49, v13, v45, v49 op_sel:[0,1,0] op_sel_hi:[0,1,0]
	v_fma_mix_f32 v18, v12, v73, 0 op_sel:[0,0,0] op_sel_hi:[0,1,0]
	v_add_f32_dpp v20, v20, v20 quad_perm:[2,3,0,1] row_mask:0xf bank_mask:0xf bound_ctrl:1
	v_fma_mix_f32 v19, v13, v73, 0 op_sel:[0,1,0] op_sel_hi:[0,1,0]
	v_fma_mix_f32 v16, v82, v78, v16 op_sel:[0,0,0] op_sel_hi:[1,1,0]
	v_add_f32_dpp v20, v20, v20 row_half_mirror row_mask:0xf bank_mask:0xf bound_ctrl:1
	v_fma_mix_f32 v17, v82, v78, v17 op_sel:[0,1,0] op_sel_hi:[1,1,0]
	v_fma_mix_f32 v18, v82, v79, v18 op_sel:[0,0,0] op_sel_hi:[1,1,0]
	v_add_f32_dpp v20, v20, v20 row_mirror row_mask:0xf bank_mask:0xf bound_ctrl:1
	v_fma_mix_f32 v19, v82, v79, v19 op_sel:[0,1,0] op_sel_hi:[1,1,0]
	v_fma_mix_f32 v10, v20, v76, v16 op_sel:[0,0,0] op_sel_hi:[0,1,0]
	v_fma_mix_f32 v11, v20, v76, v17 op_sel:[0,1,0] op_sel_hi:[0,1,0]
	v_fma_mix_f32 v12, v20, v77, v18 op_sel:[0,0,0] op_sel_hi:[0,1,0]
	v_fma_mix_f32 v13, v20, v77, v19 op_sel:[0,1,0] op_sel_hi:[0,1,0]
	s_waitcnt lgkmcnt(4)
	ds_read_b64 v[36:37], v6 offset:5136
	ds_read_b128 v[38:41], v6 offset:5392
	ds_read_b128 v[42:45], v6 offset:5648
	ds_read_u16 v46, v7 offset:5136
	v_fma_mix_f32 v14, v10, v86, 0 op_sel:[0,0,0] op_sel_hi:[0,1,0]
	v_fma_mix_f32 v50, v10, v80, 0 op_sel:[0,0,0] op_sel_hi:[0,1,0]
	v_fma_mix_f32 v14, v11, v86, v14 op_sel:[0,1,0] op_sel_hi:[0,1,0]
	v_fma_mix_f32 v50, v11, v80, v50 op_sel:[0,1,0] op_sel_hi:[0,1,0]
	v_fma_mix_f32 v14, v12, v87, v14 op_sel:[0,0,0] op_sel_hi:[0,1,0]
	v_fma_mix_f32 v50, v12, v81, v50 op_sel:[0,0,0] op_sel_hi:[0,1,0]
	v_fma_mix_f32 v14, v13, v87, v14 op_sel:[0,1,0] op_sel_hi:[0,1,0]
	v_fma_mix_f32 v16, v10, v84, 0 op_sel:[0,0,0] op_sel_hi:[0,1,0]
	v_fma_mix_f32 v17, v11, v84, 0 op_sel:[0,1,0] op_sel_hi:[0,1,0]
	v_add_f32_dpp v20, v14, v14 quad_perm:[1,0,3,2] row_mask:0xf bank_mask:0xf bound_ctrl:1
	v_fma_mix_f32 v50, v13, v81, v50 op_sel:[0,1,0] op_sel_hi:[0,1,0]
	v_fma_mix_f32 v18, v12, v85, 0 op_sel:[0,0,0] op_sel_hi:[0,1,0]
	v_add_f32_dpp v20, v20, v20 quad_perm:[2,3,0,1] row_mask:0xf bank_mask:0xf bound_ctrl:1
	v_fma_mix_f32 v19, v13, v85, 0 op_sel:[0,1,0] op_sel_hi:[0,1,0]
	v_fma_mix_f32 v16, v94, v90, v16 op_sel:[0,0,0] op_sel_hi:[1,1,0]
	v_add_f32_dpp v20, v20, v20 row_half_mirror row_mask:0xf bank_mask:0xf bound_ctrl:1
	v_fma_mix_f32 v17, v94, v90, v17 op_sel:[0,1,0] op_sel_hi:[1,1,0]
	v_fma_mix_f32 v18, v94, v91, v18 op_sel:[0,0,0] op_sel_hi:[1,1,0]
	v_add_f32_dpp v20, v20, v20 row_mirror row_mask:0xf bank_mask:0xf bound_ctrl:1
	v_fma_mix_f32 v19, v94, v91, v19 op_sel:[0,1,0] op_sel_hi:[1,1,0]
	v_fma_mix_f32 v10, v20, v88, v16 op_sel:[0,0,0] op_sel_hi:[0,1,0]
	v_fma_mix_f32 v11, v20, v88, v17 op_sel:[0,1,0] op_sel_hi:[0,1,0]
	v_fma_mix_f32 v12, v20, v89, v18 op_sel:[0,0,0] op_sel_hi:[0,1,0]
	v_fma_mix_f32 v13, v20, v89, v19 op_sel:[0,1,0] op_sel_hi:[0,1,0]
	s_waitcnt lgkmcnt(4)
	ds_read_b64 v[72:73], v6 offset:6160
	ds_read_b128 v[74:77], v6 offset:6416
	ds_read_b128 v[78:81], v6 offset:6672
	ds_read_u16 v82, v7 offset:6160
	v_fma_mix_f32 v14, v10, v26, 0 op_sel:[0,0,0] op_sel_hi:[0,1,0]
	v_fma_mix_f32 v51, v10, v92, 0 op_sel:[0,0,0] op_sel_hi:[0,1,0]
	v_fma_mix_f32 v14, v11, v26, v14 op_sel:[0,1,0] op_sel_hi:[0,1,0]
	v_fma_mix_f32 v51, v11, v92, v51 op_sel:[0,1,0] op_sel_hi:[0,1,0]
	v_fma_mix_f32 v14, v12, v27, v14 op_sel:[0,0,0] op_sel_hi:[0,1,0]
	v_fma_mix_f32 v51, v12, v93, v51 op_sel:[0,0,0] op_sel_hi:[0,1,0]
	v_fma_mix_f32 v14, v13, v27, v14 op_sel:[0,1,0] op_sel_hi:[0,1,0]
	v_fma_mix_f32 v16, v10, v24, 0 op_sel:[0,0,0] op_sel_hi:[0,1,0]
	v_fma_mix_f32 v17, v11, v24, 0 op_sel:[0,1,0] op_sel_hi:[0,1,0]
	v_add_f32_dpp v20, v14, v14 quad_perm:[1,0,3,2] row_mask:0xf bank_mask:0xf bound_ctrl:1
	v_fma_mix_f32 v51, v13, v93, v51 op_sel:[0,1,0] op_sel_hi:[0,1,0]
	v_fma_mix_f32 v18, v12, v25, 0 op_sel:[0,0,0] op_sel_hi:[0,1,0]
	v_add_f32_dpp v20, v20, v20 quad_perm:[2,3,0,1] row_mask:0xf bank_mask:0xf bound_ctrl:1
	v_fma_mix_f32 v19, v13, v25, 0 op_sel:[0,1,0] op_sel_hi:[0,1,0]
	v_fma_mix_f32 v16, v34, v30, v16 op_sel:[0,0,0] op_sel_hi:[1,1,0]
	v_add_f32_dpp v20, v20, v20 row_half_mirror row_mask:0xf bank_mask:0xf bound_ctrl:1
	v_fma_mix_f32 v17, v34, v30, v17 op_sel:[0,1,0] op_sel_hi:[1,1,0]
	v_fma_mix_f32 v18, v34, v31, v18 op_sel:[0,0,0] op_sel_hi:[1,1,0]
	v_add_f32_dpp v20, v20, v20 row_mirror row_mask:0xf bank_mask:0xf bound_ctrl:1
	v_fma_mix_f32 v19, v34, v31, v19 op_sel:[0,1,0] op_sel_hi:[1,1,0]
	v_fma_mix_f32 v10, v20, v28, v16 op_sel:[0,0,0] op_sel_hi:[0,1,0]
	v_fma_mix_f32 v11, v20, v28, v17 op_sel:[0,1,0] op_sel_hi:[0,1,0]
	v_fma_mix_f32 v12, v20, v29, v18 op_sel:[0,0,0] op_sel_hi:[0,1,0]
	v_fma_mix_f32 v13, v20, v29, v19 op_sel:[0,1,0] op_sel_hi:[0,1,0]
	s_waitcnt lgkmcnt(4)
	ds_read_b64 v[84:85], v6 offset:7184
	ds_read_b128 v[86:89], v6 offset:7440
	ds_read_b128 v[90:93], v6 offset:7696
	ds_read_u16 v94, v7 offset:7184
	v_fma_mix_f32 v14, v10, v38, 0 op_sel:[0,0,0] op_sel_hi:[0,1,0]
	v_fma_mix_f32 v52, v10, v32, 0 op_sel:[0,0,0] op_sel_hi:[0,1,0]
	v_fma_mix_f32 v14, v11, v38, v14 op_sel:[0,1,0] op_sel_hi:[0,1,0]
	v_fma_mix_f32 v52, v11, v32, v52 op_sel:[0,1,0] op_sel_hi:[0,1,0]
	v_fma_mix_f32 v14, v12, v39, v14 op_sel:[0,0,0] op_sel_hi:[0,1,0]
	v_fma_mix_f32 v52, v12, v33, v52 op_sel:[0,0,0] op_sel_hi:[0,1,0]
	v_fma_mix_f32 v14, v13, v39, v14 op_sel:[0,1,0] op_sel_hi:[0,1,0]
	v_fma_mix_f32 v16, v10, v36, 0 op_sel:[0,0,0] op_sel_hi:[0,1,0]
	v_fma_mix_f32 v17, v11, v36, 0 op_sel:[0,1,0] op_sel_hi:[0,1,0]
	v_add_f32_dpp v20, v14, v14 quad_perm:[1,0,3,2] row_mask:0xf bank_mask:0xf bound_ctrl:1
	v_fma_mix_f32 v52, v13, v33, v52 op_sel:[0,1,0] op_sel_hi:[0,1,0]
	v_fma_mix_f32 v18, v12, v37, 0 op_sel:[0,0,0] op_sel_hi:[0,1,0]
	v_add_f32_dpp v20, v20, v20 quad_perm:[2,3,0,1] row_mask:0xf bank_mask:0xf bound_ctrl:1
	v_fma_mix_f32 v19, v13, v37, 0 op_sel:[0,1,0] op_sel_hi:[0,1,0]
	v_fma_mix_f32 v16, v46, v42, v16 op_sel:[0,0,0] op_sel_hi:[1,1,0]
	v_add_f32_dpp v20, v20, v20 row_half_mirror row_mask:0xf bank_mask:0xf bound_ctrl:1
	v_fma_mix_f32 v17, v46, v42, v17 op_sel:[0,1,0] op_sel_hi:[1,1,0]
	v_fma_mix_f32 v18, v46, v43, v18 op_sel:[0,0,0] op_sel_hi:[1,1,0]
	v_add_f32_dpp v20, v20, v20 row_mirror row_mask:0xf bank_mask:0xf bound_ctrl:1
	v_fma_mix_f32 v19, v46, v43, v19 op_sel:[0,1,0] op_sel_hi:[1,1,0]
	v_fma_mix_f32 v10, v20, v40, v16 op_sel:[0,0,0] op_sel_hi:[0,1,0]
	v_fma_mix_f32 v11, v20, v40, v17 op_sel:[0,1,0] op_sel_hi:[0,1,0]
	v_fma_mix_f32 v12, v20, v41, v18 op_sel:[0,0,0] op_sel_hi:[0,1,0]
	v_fma_mix_f32 v13, v20, v41, v19 op_sel:[0,1,0] op_sel_hi:[0,1,0]
	s_waitcnt lgkmcnt(4)
	ds_read_b64 v[24:25], v6 offset:8208
	ds_read_b128 v[26:29], v6 offset:8464
	ds_read_b128 v[30:33], v6 offset:8720
	ds_read_u16 v34, v7 offset:8208
	v_fma_mix_f32 v14, v10, v74, 0 op_sel:[0,0,0] op_sel_hi:[0,1,0]
	v_fma_mix_f32 v53, v10, v44, 0 op_sel:[0,0,0] op_sel_hi:[0,1,0]
	v_fma_mix_f32 v14, v11, v74, v14 op_sel:[0,1,0] op_sel_hi:[0,1,0]
	v_fma_mix_f32 v53, v11, v44, v53 op_sel:[0,1,0] op_sel_hi:[0,1,0]
	v_fma_mix_f32 v14, v12, v75, v14 op_sel:[0,0,0] op_sel_hi:[0,1,0]
	v_fma_mix_f32 v53, v12, v45, v53 op_sel:[0,0,0] op_sel_hi:[0,1,0]
	v_fma_mix_f32 v14, v13, v75, v14 op_sel:[0,1,0] op_sel_hi:[0,1,0]
	v_fma_mix_f32 v16, v10, v72, 0 op_sel:[0,0,0] op_sel_hi:[0,1,0]
	v_fma_mix_f32 v17, v11, v72, 0 op_sel:[0,1,0] op_sel_hi:[0,1,0]
	v_add_f32_dpp v20, v14, v14 quad_perm:[1,0,3,2] row_mask:0xf bank_mask:0xf bound_ctrl:1
	v_fma_mix_f32 v53, v13, v45, v53 op_sel:[0,1,0] op_sel_hi:[0,1,0]
	v_fma_mix_f32 v18, v12, v73, 0 op_sel:[0,0,0] op_sel_hi:[0,1,0]
	v_add_f32_dpp v20, v20, v20 quad_perm:[2,3,0,1] row_mask:0xf bank_mask:0xf bound_ctrl:1
	v_fma_mix_f32 v19, v13, v73, 0 op_sel:[0,1,0] op_sel_hi:[0,1,0]
	v_fma_mix_f32 v16, v82, v78, v16 op_sel:[0,0,0] op_sel_hi:[1,1,0]
	v_add_f32_dpp v20, v20, v20 row_half_mirror row_mask:0xf bank_mask:0xf bound_ctrl:1
	v_fma_mix_f32 v17, v82, v78, v17 op_sel:[0,1,0] op_sel_hi:[1,1,0]
	v_fma_mix_f32 v18, v82, v79, v18 op_sel:[0,0,0] op_sel_hi:[1,1,0]
	v_add_f32_dpp v20, v20, v20 row_mirror row_mask:0xf bank_mask:0xf bound_ctrl:1
	v_fma_mix_f32 v19, v82, v79, v19 op_sel:[0,1,0] op_sel_hi:[1,1,0]
	v_fma_mix_f32 v10, v20, v76, v16 op_sel:[0,0,0] op_sel_hi:[0,1,0]
	v_fma_mix_f32 v11, v20, v76, v17 op_sel:[0,1,0] op_sel_hi:[0,1,0]
	v_fma_mix_f32 v12, v20, v77, v18 op_sel:[0,0,0] op_sel_hi:[0,1,0]
	v_fma_mix_f32 v13, v20, v77, v19 op_sel:[0,1,0] op_sel_hi:[0,1,0]
	s_waitcnt lgkmcnt(4)
	ds_read_b64 v[36:37], v6 offset:9232
	ds_read_b128 v[38:41], v6 offset:9488
	ds_read_b128 v[42:45], v6 offset:9744
	ds_read_u16 v46, v7 offset:9232
	v_fma_mix_f32 v14, v10, v86, 0 op_sel:[0,0,0] op_sel_hi:[0,1,0]
	v_fma_mix_f32 v54, v10, v80, 0 op_sel:[0,0,0] op_sel_hi:[0,1,0]
	v_fma_mix_f32 v14, v11, v86, v14 op_sel:[0,1,0] op_sel_hi:[0,1,0]
	v_fma_mix_f32 v54, v11, v80, v54 op_sel:[0,1,0] op_sel_hi:[0,1,0]
	v_fma_mix_f32 v14, v12, v87, v14 op_sel:[0,0,0] op_sel_hi:[0,1,0]
	v_fma_mix_f32 v54, v12, v81, v54 op_sel:[0,0,0] op_sel_hi:[0,1,0]
	v_fma_mix_f32 v14, v13, v87, v14 op_sel:[0,1,0] op_sel_hi:[0,1,0]
	v_fma_mix_f32 v16, v10, v84, 0 op_sel:[0,0,0] op_sel_hi:[0,1,0]
	v_fma_mix_f32 v17, v11, v84, 0 op_sel:[0,1,0] op_sel_hi:[0,1,0]
	v_add_f32_dpp v20, v14, v14 quad_perm:[1,0,3,2] row_mask:0xf bank_mask:0xf bound_ctrl:1
	v_fma_mix_f32 v54, v13, v81, v54 op_sel:[0,1,0] op_sel_hi:[0,1,0]
	v_fma_mix_f32 v18, v12, v85, 0 op_sel:[0,0,0] op_sel_hi:[0,1,0]
	v_add_f32_dpp v20, v20, v20 quad_perm:[2,3,0,1] row_mask:0xf bank_mask:0xf bound_ctrl:1
	v_fma_mix_f32 v19, v13, v85, 0 op_sel:[0,1,0] op_sel_hi:[0,1,0]
	v_fma_mix_f32 v16, v94, v90, v16 op_sel:[0,0,0] op_sel_hi:[1,1,0]
	v_add_f32_dpp v20, v20, v20 row_half_mirror row_mask:0xf bank_mask:0xf bound_ctrl:1
	v_fma_mix_f32 v17, v94, v90, v17 op_sel:[0,1,0] op_sel_hi:[1,1,0]
	v_fma_mix_f32 v18, v94, v91, v18 op_sel:[0,0,0] op_sel_hi:[1,1,0]
	v_add_f32_dpp v20, v20, v20 row_mirror row_mask:0xf bank_mask:0xf bound_ctrl:1
	v_fma_mix_f32 v19, v94, v91, v19 op_sel:[0,1,0] op_sel_hi:[1,1,0]
	v_fma_mix_f32 v10, v20, v88, v16 op_sel:[0,0,0] op_sel_hi:[0,1,0]
	v_fma_mix_f32 v11, v20, v88, v17 op_sel:[0,1,0] op_sel_hi:[0,1,0]
	v_fma_mix_f32 v12, v20, v89, v18 op_sel:[0,0,0] op_sel_hi:[0,1,0]
	v_fma_mix_f32 v13, v20, v89, v19 op_sel:[0,1,0] op_sel_hi:[0,1,0]
	s_waitcnt lgkmcnt(4)
	ds_read_b64 v[72:73], v6 offset:10256
	ds_read_b128 v[74:77], v6 offset:10512
	ds_read_b128 v[78:81], v6 offset:10768
	ds_read_u16 v82, v7 offset:10256
	v_fma_mix_f32 v14, v10, v26, 0 op_sel:[0,0,0] op_sel_hi:[0,1,0]
	v_fma_mix_f32 v55, v10, v92, 0 op_sel:[0,0,0] op_sel_hi:[0,1,0]
	v_fma_mix_f32 v14, v11, v26, v14 op_sel:[0,1,0] op_sel_hi:[0,1,0]
	v_fma_mix_f32 v55, v11, v92, v55 op_sel:[0,1,0] op_sel_hi:[0,1,0]
	v_fma_mix_f32 v14, v12, v27, v14 op_sel:[0,0,0] op_sel_hi:[0,1,0]
	v_fma_mix_f32 v55, v12, v93, v55 op_sel:[0,0,0] op_sel_hi:[0,1,0]
	v_fma_mix_f32 v14, v13, v27, v14 op_sel:[0,1,0] op_sel_hi:[0,1,0]
	v_fma_mix_f32 v16, v10, v24, 0 op_sel:[0,0,0] op_sel_hi:[0,1,0]
	v_fma_mix_f32 v17, v11, v24, 0 op_sel:[0,1,0] op_sel_hi:[0,1,0]
	v_add_f32_dpp v20, v14, v14 quad_perm:[1,0,3,2] row_mask:0xf bank_mask:0xf bound_ctrl:1
	v_fma_mix_f32 v55, v13, v93, v55 op_sel:[0,1,0] op_sel_hi:[0,1,0]
	v_fma_mix_f32 v18, v12, v25, 0 op_sel:[0,0,0] op_sel_hi:[0,1,0]
	v_add_f32_dpp v20, v20, v20 quad_perm:[2,3,0,1] row_mask:0xf bank_mask:0xf bound_ctrl:1
	v_fma_mix_f32 v19, v13, v25, 0 op_sel:[0,1,0] op_sel_hi:[0,1,0]
	v_fma_mix_f32 v16, v34, v30, v16 op_sel:[0,0,0] op_sel_hi:[1,1,0]
	v_add_f32_dpp v20, v20, v20 row_half_mirror row_mask:0xf bank_mask:0xf bound_ctrl:1
	v_fma_mix_f32 v17, v34, v30, v17 op_sel:[0,1,0] op_sel_hi:[1,1,0]
	v_fma_mix_f32 v18, v34, v31, v18 op_sel:[0,0,0] op_sel_hi:[1,1,0]
	v_add_f32_dpp v20, v20, v20 row_mirror row_mask:0xf bank_mask:0xf bound_ctrl:1
	v_fma_mix_f32 v19, v34, v31, v19 op_sel:[0,1,0] op_sel_hi:[1,1,0]
	v_fma_mix_f32 v10, v20, v28, v16 op_sel:[0,0,0] op_sel_hi:[0,1,0]
	v_fma_mix_f32 v11, v20, v28, v17 op_sel:[0,1,0] op_sel_hi:[0,1,0]
	v_fma_mix_f32 v12, v20, v29, v18 op_sel:[0,0,0] op_sel_hi:[0,1,0]
	v_fma_mix_f32 v13, v20, v29, v19 op_sel:[0,1,0] op_sel_hi:[0,1,0]
	s_waitcnt lgkmcnt(4)
	ds_read_b64 v[84:85], v6 offset:11280
	ds_read_b128 v[86:89], v6 offset:11536
	ds_read_b128 v[90:93], v6 offset:11792
	ds_read_u16 v94, v7 offset:11280
	v_fma_mix_f32 v14, v10, v38, 0 op_sel:[0,0,0] op_sel_hi:[0,1,0]
	v_fma_mix_f32 v56, v10, v32, 0 op_sel:[0,0,0] op_sel_hi:[0,1,0]
	v_fma_mix_f32 v14, v11, v38, v14 op_sel:[0,1,0] op_sel_hi:[0,1,0]
	v_fma_mix_f32 v56, v11, v32, v56 op_sel:[0,1,0] op_sel_hi:[0,1,0]
	v_fma_mix_f32 v14, v12, v39, v14 op_sel:[0,0,0] op_sel_hi:[0,1,0]
	v_fma_mix_f32 v56, v12, v33, v56 op_sel:[0,0,0] op_sel_hi:[0,1,0]
	v_fma_mix_f32 v14, v13, v39, v14 op_sel:[0,1,0] op_sel_hi:[0,1,0]
	v_fma_mix_f32 v16, v10, v36, 0 op_sel:[0,0,0] op_sel_hi:[0,1,0]
	v_fma_mix_f32 v17, v11, v36, 0 op_sel:[0,1,0] op_sel_hi:[0,1,0]
	v_add_f32_dpp v20, v14, v14 quad_perm:[1,0,3,2] row_mask:0xf bank_mask:0xf bound_ctrl:1
	v_fma_mix_f32 v56, v13, v33, v56 op_sel:[0,1,0] op_sel_hi:[0,1,0]
	v_fma_mix_f32 v18, v12, v37, 0 op_sel:[0,0,0] op_sel_hi:[0,1,0]
	v_add_f32_dpp v20, v20, v20 quad_perm:[2,3,0,1] row_mask:0xf bank_mask:0xf bound_ctrl:1
	v_fma_mix_f32 v19, v13, v37, 0 op_sel:[0,1,0] op_sel_hi:[0,1,0]
	v_fma_mix_f32 v16, v46, v42, v16 op_sel:[0,0,0] op_sel_hi:[1,1,0]
	v_add_f32_dpp v20, v20, v20 row_half_mirror row_mask:0xf bank_mask:0xf bound_ctrl:1
	v_fma_mix_f32 v17, v46, v42, v17 op_sel:[0,1,0] op_sel_hi:[1,1,0]
	v_fma_mix_f32 v18, v46, v43, v18 op_sel:[0,0,0] op_sel_hi:[1,1,0]
	v_add_f32_dpp v20, v20, v20 row_mirror row_mask:0xf bank_mask:0xf bound_ctrl:1
	v_fma_mix_f32 v19, v46, v43, v19 op_sel:[0,1,0] op_sel_hi:[1,1,0]
	v_fma_mix_f32 v10, v20, v40, v16 op_sel:[0,0,0] op_sel_hi:[0,1,0]
	v_fma_mix_f32 v11, v20, v40, v17 op_sel:[0,1,0] op_sel_hi:[0,1,0]
	v_fma_mix_f32 v12, v20, v41, v18 op_sel:[0,0,0] op_sel_hi:[0,1,0]
	v_fma_mix_f32 v13, v20, v41, v19 op_sel:[0,1,0] op_sel_hi:[0,1,0]
	s_waitcnt lgkmcnt(4)
	ds_read_b64 v[24:25], v6 offset:12304
	ds_read_b128 v[26:29], v6 offset:12560
	ds_read_b128 v[30:33], v6 offset:12816
	ds_read_u16 v34, v7 offset:12304
	v_fma_mix_f32 v14, v10, v74, 0 op_sel:[0,0,0] op_sel_hi:[0,1,0]
	v_fma_mix_f32 v57, v10, v44, 0 op_sel:[0,0,0] op_sel_hi:[0,1,0]
	v_fma_mix_f32 v14, v11, v74, v14 op_sel:[0,1,0] op_sel_hi:[0,1,0]
	v_fma_mix_f32 v57, v11, v44, v57 op_sel:[0,1,0] op_sel_hi:[0,1,0]
	v_fma_mix_f32 v14, v12, v75, v14 op_sel:[0,0,0] op_sel_hi:[0,1,0]
	v_fma_mix_f32 v57, v12, v45, v57 op_sel:[0,0,0] op_sel_hi:[0,1,0]
	v_fma_mix_f32 v14, v13, v75, v14 op_sel:[0,1,0] op_sel_hi:[0,1,0]
	v_fma_mix_f32 v16, v10, v72, 0 op_sel:[0,0,0] op_sel_hi:[0,1,0]
	v_fma_mix_f32 v17, v11, v72, 0 op_sel:[0,1,0] op_sel_hi:[0,1,0]
	v_add_f32_dpp v20, v14, v14 quad_perm:[1,0,3,2] row_mask:0xf bank_mask:0xf bound_ctrl:1
	v_fma_mix_f32 v57, v13, v45, v57 op_sel:[0,1,0] op_sel_hi:[0,1,0]
	v_fma_mix_f32 v18, v12, v73, 0 op_sel:[0,0,0] op_sel_hi:[0,1,0]
	v_add_f32_dpp v20, v20, v20 quad_perm:[2,3,0,1] row_mask:0xf bank_mask:0xf bound_ctrl:1
	v_fma_mix_f32 v19, v13, v73, 0 op_sel:[0,1,0] op_sel_hi:[0,1,0]
	v_fma_mix_f32 v16, v82, v78, v16 op_sel:[0,0,0] op_sel_hi:[1,1,0]
	v_add_f32_dpp v20, v20, v20 row_half_mirror row_mask:0xf bank_mask:0xf bound_ctrl:1
	v_fma_mix_f32 v17, v82, v78, v17 op_sel:[0,1,0] op_sel_hi:[1,1,0]
	v_fma_mix_f32 v18, v82, v79, v18 op_sel:[0,0,0] op_sel_hi:[1,1,0]
	v_add_f32_dpp v20, v20, v20 row_mirror row_mask:0xf bank_mask:0xf bound_ctrl:1
	v_fma_mix_f32 v19, v82, v79, v19 op_sel:[0,1,0] op_sel_hi:[1,1,0]
	v_fma_mix_f32 v10, v20, v76, v16 op_sel:[0,0,0] op_sel_hi:[0,1,0]
	v_fma_mix_f32 v11, v20, v76, v17 op_sel:[0,1,0] op_sel_hi:[0,1,0]
	v_fma_mix_f32 v12, v20, v77, v18 op_sel:[0,0,0] op_sel_hi:[0,1,0]
	v_fma_mix_f32 v13, v20, v77, v19 op_sel:[0,1,0] op_sel_hi:[0,1,0]
	s_waitcnt lgkmcnt(4)
	ds_read_b64 v[36:37], v6 offset:13328
	ds_read_b128 v[38:41], v6 offset:13584
	ds_read_b128 v[42:45], v6 offset:13840
	ds_read_u16 v46, v7 offset:13328
	v_fma_mix_f32 v14, v10, v86, 0 op_sel:[0,0,0] op_sel_hi:[0,1,0]
	v_fma_mix_f32 v58, v10, v80, 0 op_sel:[0,0,0] op_sel_hi:[0,1,0]
	v_fma_mix_f32 v14, v11, v86, v14 op_sel:[0,1,0] op_sel_hi:[0,1,0]
	v_fma_mix_f32 v58, v11, v80, v58 op_sel:[0,1,0] op_sel_hi:[0,1,0]
	v_fma_mix_f32 v14, v12, v87, v14 op_sel:[0,0,0] op_sel_hi:[0,1,0]
	v_fma_mix_f32 v58, v12, v81, v58 op_sel:[0,0,0] op_sel_hi:[0,1,0]
	v_fma_mix_f32 v14, v13, v87, v14 op_sel:[0,1,0] op_sel_hi:[0,1,0]
	v_fma_mix_f32 v16, v10, v84, 0 op_sel:[0,0,0] op_sel_hi:[0,1,0]
	v_fma_mix_f32 v17, v11, v84, 0 op_sel:[0,1,0] op_sel_hi:[0,1,0]
	v_add_f32_dpp v20, v14, v14 quad_perm:[1,0,3,2] row_mask:0xf bank_mask:0xf bound_ctrl:1
	v_fma_mix_f32 v58, v13, v81, v58 op_sel:[0,1,0] op_sel_hi:[0,1,0]
	v_fma_mix_f32 v18, v12, v85, 0 op_sel:[0,0,0] op_sel_hi:[0,1,0]
	v_add_f32_dpp v20, v20, v20 quad_perm:[2,3,0,1] row_mask:0xf bank_mask:0xf bound_ctrl:1
	v_fma_mix_f32 v19, v13, v85, 0 op_sel:[0,1,0] op_sel_hi:[0,1,0]
	v_fma_mix_f32 v16, v94, v90, v16 op_sel:[0,0,0] op_sel_hi:[1,1,0]
	v_add_f32_dpp v20, v20, v20 row_half_mirror row_mask:0xf bank_mask:0xf bound_ctrl:1
	v_fma_mix_f32 v17, v94, v90, v17 op_sel:[0,1,0] op_sel_hi:[1,1,0]
	v_fma_mix_f32 v18, v94, v91, v18 op_sel:[0,0,0] op_sel_hi:[1,1,0]
	v_add_f32_dpp v20, v20, v20 row_mirror row_mask:0xf bank_mask:0xf bound_ctrl:1
	v_fma_mix_f32 v19, v94, v91, v19 op_sel:[0,1,0] op_sel_hi:[1,1,0]
	v_fma_mix_f32 v10, v20, v88, v16 op_sel:[0,0,0] op_sel_hi:[0,1,0]
	v_fma_mix_f32 v11, v20, v88, v17 op_sel:[0,1,0] op_sel_hi:[0,1,0]
	v_fma_mix_f32 v12, v20, v89, v18 op_sel:[0,0,0] op_sel_hi:[0,1,0]
	v_fma_mix_f32 v13, v20, v89, v19 op_sel:[0,1,0] op_sel_hi:[0,1,0]
	s_waitcnt lgkmcnt(4)
	ds_read_b64 v[72:73], v6 offset:14352
	ds_read_b128 v[74:77], v6 offset:14608
	ds_read_b128 v[78:81], v6 offset:14864
	ds_read_u16 v82, v7 offset:14352
	v_fma_mix_f32 v14, v10, v26, 0 op_sel:[0,0,0] op_sel_hi:[0,1,0]
	v_fma_mix_f32 v59, v10, v92, 0 op_sel:[0,0,0] op_sel_hi:[0,1,0]
	v_fma_mix_f32 v14, v11, v26, v14 op_sel:[0,1,0] op_sel_hi:[0,1,0]
	v_fma_mix_f32 v59, v11, v92, v59 op_sel:[0,1,0] op_sel_hi:[0,1,0]
	v_fma_mix_f32 v14, v12, v27, v14 op_sel:[0,0,0] op_sel_hi:[0,1,0]
	v_fma_mix_f32 v59, v12, v93, v59 op_sel:[0,0,0] op_sel_hi:[0,1,0]
	v_fma_mix_f32 v14, v13, v27, v14 op_sel:[0,1,0] op_sel_hi:[0,1,0]
	v_fma_mix_f32 v16, v10, v24, 0 op_sel:[0,0,0] op_sel_hi:[0,1,0]
	v_fma_mix_f32 v17, v11, v24, 0 op_sel:[0,1,0] op_sel_hi:[0,1,0]
	v_add_f32_dpp v20, v14, v14 quad_perm:[1,0,3,2] row_mask:0xf bank_mask:0xf bound_ctrl:1
	v_fma_mix_f32 v59, v13, v93, v59 op_sel:[0,1,0] op_sel_hi:[0,1,0]
	v_fma_mix_f32 v18, v12, v25, 0 op_sel:[0,0,0] op_sel_hi:[0,1,0]
	v_add_f32_dpp v20, v20, v20 quad_perm:[2,3,0,1] row_mask:0xf bank_mask:0xf bound_ctrl:1
	v_fma_mix_f32 v19, v13, v25, 0 op_sel:[0,1,0] op_sel_hi:[0,1,0]
	v_fma_mix_f32 v16, v34, v30, v16 op_sel:[0,0,0] op_sel_hi:[1,1,0]
	v_add_f32_dpp v20, v20, v20 row_half_mirror row_mask:0xf bank_mask:0xf bound_ctrl:1
	v_fma_mix_f32 v17, v34, v30, v17 op_sel:[0,1,0] op_sel_hi:[1,1,0]
	v_fma_mix_f32 v18, v34, v31, v18 op_sel:[0,0,0] op_sel_hi:[1,1,0]
	v_add_f32_dpp v20, v20, v20 row_mirror row_mask:0xf bank_mask:0xf bound_ctrl:1
	v_fma_mix_f32 v19, v34, v31, v19 op_sel:[0,1,0] op_sel_hi:[1,1,0]
	v_fma_mix_f32 v10, v20, v28, v16 op_sel:[0,0,0] op_sel_hi:[0,1,0]
	v_fma_mix_f32 v11, v20, v28, v17 op_sel:[0,1,0] op_sel_hi:[0,1,0]
	v_fma_mix_f32 v12, v20, v29, v18 op_sel:[0,0,0] op_sel_hi:[0,1,0]
	v_fma_mix_f32 v13, v20, v29, v19 op_sel:[0,1,0] op_sel_hi:[0,1,0]
	s_waitcnt lgkmcnt(4)
; DEVINL u16 f2bf(float a) { return (u16)(pk2(a, 0.f) & 0xffffu); }
; #define RW_STEP2(B) RW_STEP(B, WvA, XA, KrA, vhA, WvB, XB, KrB, vhB); RW_STEP((B) + 1, WvB, XB, KrB, vhB, WvA, XA, KrA, vhA)
; #define RW_STEP4(B) RW_STEP2(B); RW_STEP2((B) + 2)
; template <int DIR>
; DEVINL void rwkv_scan_dir(const Params& p, int task, int lane, int wave) {
;     ...
; #pragma unroll 1
;   for (int st = 0; st < 4096; st += 32) {
;     RW_STEP(0, WvA, XA, KrA, vhA, WvB, XB, KrB, vhB);
;     if (st > 0) { const int q0 = st - 16 + seg; yo[(long)(DIR ? (4095 - q0) : q0) * 1024] = f2bf(ykeep); }
;     RW_STEP(1, WvB, XB, KrB, vhB, WvA, XA, KrA, vhA);
;     RW_STEP2(2); RW_STEP4(4); RW_STEP4(8); RW_STEP4(12);
;     RW_STEP(16, WvA, XA, KrA, vhA, WvB, XB, KrB, vhB);
;     { const int q0 = st + seg; yo[(long)(DIR ? (4095 - q0) : q0) * 1024] = f2bf(ykeep); }
;     RW_STEP(17, WvB, XB, KrB, vhB, WvA, XA, KrA, vhA);
;     RW_STEP2(18); RW_STEP4(20); RW_STEP4(24); RW_STEP4(28);
;   }
	ds_read_b128 v[100:103], v9
	ds_read_b128 v[104:107], v9 offset:16
	ds_read_b64 v[84:85], v6 offset:15376
	ds_read_b128 v[86:89], v6 offset:15632
	ds_read_b128 v[90:93], v6 offset:15888
	ds_read_u16 v94, v7 offset:15376
	v_fma_mix_f32 v14, v10, v38, 0 op_sel:[0,0,0] op_sel_hi:[0,1,0]
	v_fma_mix_f32 v60, v10, v32, 0 op_sel:[0,0,0] op_sel_hi:[0,1,0]
	v_fma_mix_f32 v14, v11, v38, v14 op_sel:[0,1,0] op_sel_hi:[0,1,0]
	v_fma_mix_f32 v60, v11, v32, v60 op_sel:[0,1,0] op_sel_hi:[0,1,0]
	v_fma_mix_f32 v14, v12, v39, v14 op_sel:[0,0,0] op_sel_hi:[0,1,0]
	v_fma_mix_f32 v60, v12, v33, v60 op_sel:[0,0,0] op_sel_hi:[0,1,0]
	v_fma_mix_f32 v14, v13, v39, v14 op_sel:[0,1,0] op_sel_hi:[0,1,0]
	v_fma_mix_f32 v16, v10, v36, 0 op_sel:[0,0,0] op_sel_hi:[0,1,0]
	v_fma_mix_f32 v17, v11, v36, 0 op_sel:[0,1,0] op_sel_hi:[0,1,0]
	v_add_f32_dpp v20, v14, v14 quad_perm:[1,0,3,2] row_mask:0xf bank_mask:0xf bound_ctrl:1
	v_fma_mix_f32 v60, v13, v33, v60 op_sel:[0,1,0] op_sel_hi:[0,1,0]
	v_fma_mix_f32 v18, v12, v37, 0 op_sel:[0,0,0] op_sel_hi:[0,1,0]
	v_add_f32_dpp v20, v20, v20 quad_perm:[2,3,0,1] row_mask:0xf bank_mask:0xf bound_ctrl:1
	v_fma_mix_f32 v19, v13, v37, 0 op_sel:[0,1,0] op_sel_hi:[0,1,0]
	v_fma_mix_f32 v16, v46, v42, v16 op_sel:[0,0,0] op_sel_hi:[1,1,0]
	v_add_f32_dpp v20, v20, v20 row_half_mirror row_mask:0xf bank_mask:0xf bound_ctrl:1
	v_fma_mix_f32 v17, v46, v42, v17 op_sel:[0,1,0] op_sel_hi:[1,1,0]
	v_fma_mix_f32 v18, v46, v43, v18 op_sel:[0,0,0] op_sel_hi:[1,1,0]
	v_add_f32_dpp v20, v20, v20 row_mirror row_mask:0xf bank_mask:0xf bound_ctrl:1
	v_fma_mix_f32 v19, v46, v43, v19 op_sel:[0,1,0] op_sel_hi:[1,1,0]
	v_fma_mix_f32 v10, v20, v40, v16 op_sel:[0,0,0] op_sel_hi:[0,1,0]
	v_fma_mix_f32 v11, v20, v40, v17 op_sel:[0,1,0] op_sel_hi:[0,1,0]
	v_fma_mix_f32 v12, v20, v41, v18 op_sel:[0,0,0] op_sel_hi:[0,1,0]
	v_fma_mix_f32 v13, v20, v41, v19 op_sel:[0,1,0] op_sel_hi:[0,1,0]
	s_waitcnt lgkmcnt(4)
	v_add_u32_e32 v6, 0x4000, v6
	v_add_u32_e32 v7, 0x4000, v7
	v_and_b32_e32 v6, 0x1ffff, v6
	v_and_b32_e32 v7, 0x1ffff, v7
	ds_read_b64 v[24:25], v6 offset:16
	ds_read_b128 v[26:29], v6 offset:272
	ds_read_b128 v[30:33], v6 offset:528
	ds_read_u16 v34, v7 offset:16
	v_fma_mix_f32 v14, v10, v74, 0 op_sel:[0,0,0] op_sel_hi:[0,1,0]
	v_fma_mix_f32 v61, v10, v44, 0 op_sel:[0,0,0] op_sel_hi:[0,1,0]
	v_fma_mix_f32 v14, v11, v74, v14 op_sel:[0,1,0] op_sel_hi:[0,1,0]
	v_fma_mix_f32 v61, v11, v44, v61 op_sel:[0,1,0] op_sel_hi:[0,1,0]
	v_fma_mix_f32 v14, v12, v75, v14 op_sel:[0,0,0] op_sel_hi:[0,1,0]
	v_fma_mix_f32 v61, v12, v45, v61 op_sel:[0,0,0] op_sel_hi:[0,1,0]
	v_fma_mix_f32 v14, v13, v75, v14 op_sel:[0,1,0] op_sel_hi:[0,1,0]
	v_fma_mix_f32 v16, v10, v72, 0 op_sel:[0,0,0] op_sel_hi:[0,1,0]
	v_fma_mix_f32 v17, v11, v72, 0 op_sel:[0,1,0] op_sel_hi:[0,1,0]
	v_add_f32_dpp v20, v14, v14 quad_perm:[1,0,3,2] row_mask:0xf bank_mask:0xf bound_ctrl:1
	v_fma_mix_f32 v61, v13, v45, v61 op_sel:[0,1,0] op_sel_hi:[0,1,0]
	v_fma_mix_f32 v18, v12, v73, 0 op_sel:[0,0,0] op_sel_hi:[0,1,0]
	v_add_f32_dpp v20, v20, v20 quad_perm:[2,3,0,1] row_mask:0xf bank_mask:0xf bound_ctrl:1
	v_fma_mix_f32 v19, v13, v73, 0 op_sel:[0,1,0] op_sel_hi:[0,1,0]
	v_fma_mix_f32 v16, v82, v78, v16 op_sel:[0,0,0] op_sel_hi:[1,1,0]
	v_add_f32_dpp v20, v20, v20 row_half_mirror row_mask:0xf bank_mask:0xf bound_ctrl:1
	v_fma_mix_f32 v17, v82, v78, v17 op_sel:[0,1,0] op_sel_hi:[1,1,0]
	v_fma_mix_f32 v18, v82, v79, v18 op_sel:[0,0,0] op_sel_hi:[1,1,0]
	v_add_f32_dpp v20, v20, v20 row_mirror row_mask:0xf bank_mask:0xf bound_ctrl:1
	v_fma_mix_f32 v19, v82, v79, v19 op_sel:[0,1,0] op_sel_hi:[1,1,0]
	v_fma_mix_f32 v10, v20, v76, v16 op_sel:[0,0,0] op_sel_hi:[0,1,0]
	v_fma_mix_f32 v11, v20, v76, v17 op_sel:[0,1,0] op_sel_hi:[0,1,0]
	v_fma_mix_f32 v12, v20, v77, v18 op_sel:[0,0,0] op_sel_hi:[0,1,0]
	v_fma_mix_f32 v13, v20, v77, v19 op_sel:[0,1,0] op_sel_hi:[0,1,0]
	s_waitcnt lgkmcnt(4)
	ds_read_b64 v[36:37], v6 offset:1040
	ds_read_b128 v[38:41], v6 offset:1296
	ds_read_b128 v[42:45], v6 offset:1552
	ds_read_u16 v46, v7 offset:1040
	v_fma_mix_f32 v14, v10, v86, 0 op_sel:[0,0,0] op_sel_hi:[0,1,0]
	v_fma_mix_f32 v62, v10, v80, 0 op_sel:[0,0,0] op_sel_hi:[0,1,0]
	v_fma_mix_f32 v14, v11, v86, v14 op_sel:[0,1,0] op_sel_hi:[0,1,0]
	v_fma_mix_f32 v62, v11, v80, v62 op_sel:[0,1,0] op_sel_hi:[0,1,0]
	v_fma_mix_f32 v14, v12, v87, v14 op_sel:[0,0,0] op_sel_hi:[0,1,0]
	v_fma_mix_f32 v62, v12, v81, v62 op_sel:[0,0,0] op_sel_hi:[0,1,0]
	v_fma_mix_f32 v14, v13, v87, v14 op_sel:[0,1,0] op_sel_hi:[0,1,0]
	v_fma_mix_f32 v16, v10, v84, 0 op_sel:[0,0,0] op_sel_hi:[0,1,0]
	v_fma_mix_f32 v17, v11, v84, 0 op_sel:[0,1,0] op_sel_hi:[0,1,0]
	v_add_f32_dpp v20, v14, v14 quad_perm:[1,0,3,2] row_mask:0xf bank_mask:0xf bound_ctrl:1
	v_fma_mix_f32 v62, v13, v81, v62 op_sel:[0,1,0] op_sel_hi:[0,1,0]
	v_fma_mix_f32 v18, v12, v85, 0 op_sel:[0,0,0] op_sel_hi:[0,1,0]
	v_add_f32_dpp v20, v20, v20 quad_perm:[2,3,0,1] row_mask:0xf bank_mask:0xf bound_ctrl:1
	v_fma_mix_f32 v19, v13, v85, 0 op_sel:[0,1,0] op_sel_hi:[0,1,0]
	v_fma_mix_f32 v16, v94, v90, v16 op_sel:[0,0,0] op_sel_hi:[1,1,0]
	v_add_f32_dpp v20, v20, v20 row_half_mirror row_mask:0xf bank_mask:0xf bound_ctrl:1
	v_fma_mix_f32 v17, v94, v90, v17 op_sel:[0,1,0] op_sel_hi:[1,1,0]
	v_fma_mix_f32 v18, v94, v91, v18 op_sel:[0,0,0] op_sel_hi:[1,1,0]
	v_add_f32_dpp v20, v20, v20 row_mirror row_mask:0xf bank_mask:0xf bound_ctrl:1
	v_fma_mix_f32 v19, v94, v91, v19 op_sel:[0,1,0] op_sel_hi:[1,1,0]
	v_fma_mix_f32 v10, v20, v88, v16 op_sel:[0,0,0] op_sel_hi:[0,1,0]
	v_fma_mix_f32 v11, v20, v88, v17 op_sel:[0,1,0] op_sel_hi:[0,1,0]
	v_fma_mix_f32 v12, v20, v89, v18 op_sel:[0,0,0] op_sel_hi:[0,1,0]
	v_fma_mix_f32 v13, v20, v89, v19 op_sel:[0,1,0] op_sel_hi:[0,1,0]
	s_waitcnt lgkmcnt(4)
	s_add_u32 s15, s15, 1
	s_add_u32 s14, s14, 1
	v_mov_b32_e32 v69, s15
	ds_write_b32 v68, v69
	s_cmp_lt_u32 s14, 0x100
	s_cbranch_scc1 .Lrw_blk_d0
; DEVINL u16 f2bf(float a) { return (u16)(pk2(a, 0.f) & 0xffffu); }
; #define RW_STEP2(B) RW_STEP(B, WvA, XA, KrA, vhA, WvB, XB, KrB, vhB); RW_STEP((B) + 1, WvB, XB, KrB, vhB, WvA, XA, KrA, vhA)
; #define RW_STEP4(B) RW_STEP2(B); RW_STEP2((B) + 2)
; template <int DIR>
; DEVINL void rwkv_scan_dir(const Params& p, int task, int lane, int wave) {
;     ...
;     { const int q0 = st + seg; yo[(long)(DIR ? (4095 - q0) : q0) * 1024] = f2bf(ykeep); }
;     RW_STEP(17, WvB, XB, KrB, vhB, WvA, XA, KrA, vhA);
;     RW_STEP2(18); RW_STEP4(20); RW_STEP4(24); RW_STEP4(28);
;   }
;   {
;     const float ylast = allred16(ypart);
;     ykeep = (seg == 15) ? ylast : ykeep;
;     const int q0 = 4096 - 16 + seg; yo[(long)(DIR ? (4095 - q0) : q0) * 1024] = f2bf(ykeep);
;   }
	v_fma_mix_f32 v21, v10, v92, 0 op_sel:[0,0,0] op_sel_hi:[0,1,0]
	v_fma_mix_f32 v22, v12, v93, 0 op_sel:[0,0,0] op_sel_hi:[0,1,0]
	v_fma_mix_f32 v21, v11, v92, v21 op_sel:[0,1,0] op_sel_hi:[0,1,0]
	v_fma_mix_f32 v22, v13, v93, v22 op_sel:[0,1,0] op_sel_hi:[0,1,0]
	v_add_f32_e32 v63, v21, v22
	s_nop 1
	v_add_f32_dpp v48, v48, v48 row_ror:8 row_mask:0xf bank_mask:0x3
	v_add_f32_dpp v49, v49, v49 row_ror:8 row_mask:0xf bank_mask:0x3
	v_add_f32_dpp v50, v50, v50 row_ror:8 row_mask:0xf bank_mask:0x3
	v_add_f32_dpp v51, v51, v51 row_ror:8 row_mask:0xf bank_mask:0x3
	v_add_f32_dpp v52, v52, v52 row_ror:8 row_mask:0xf bank_mask:0x3
	v_add_f32_dpp v53, v53, v53 row_ror:8 row_mask:0xf bank_mask:0x3
	v_add_f32_dpp v54, v54, v54 row_ror:8 row_mask:0xf bank_mask:0x3
	v_add_f32_dpp v55, v55, v55 row_ror:8 row_mask:0xf bank_mask:0x3
	v_add_f32_dpp v48, v56, v56 row_ror:8 row_mask:0xf bank_mask:0xc
	v_add_f32_dpp v49, v57, v57 row_ror:8 row_mask:0xf bank_mask:0xc
	v_add_f32_dpp v50, v58, v58 row_ror:8 row_mask:0xf bank_mask:0xc
	v_add_f32_dpp v51, v59, v59 row_ror:8 row_mask:0xf bank_mask:0xc
	v_add_f32_dpp v52, v60, v60 row_ror:8 row_mask:0xf bank_mask:0xc
	v_add_f32_dpp v53, v61, v61 row_ror:8 row_mask:0xf bank_mask:0xc
	v_add_f32_dpp v54, v62, v62 row_ror:8 row_mask:0xf bank_mask:0xc
	v_add_f32_dpp v55, v63, v63 row_ror:8 row_mask:0xf bank_mask:0xc
	v_add_f32_dpp v48, v48, v48 row_ror:12 row_mask:0xf bank_mask:0x5
	v_add_f32_dpp v49, v49, v49 row_ror:12 row_mask:0xf bank_mask:0x5
	v_add_f32_dpp v50, v50, v50 row_ror:12 row_mask:0xf bank_mask:0x5
	v_add_f32_dpp v51, v51, v51 row_ror:12 row_mask:0xf bank_mask:0x5
	v_add_f32_dpp v48, v52, v52 row_ror:4 row_mask:0xf bank_mask:0xa
	v_add_f32_dpp v49, v53, v53 row_ror:4 row_mask:0xf bank_mask:0xa
	v_add_f32_dpp v50, v54, v54 row_ror:4 row_mask:0xf bank_mask:0xa
	v_add_f32_dpp v51, v55, v55 row_ror:4 row_mask:0xf bank_mask:0xa
	v_add_f32_dpp v64, v48, v48 quad_perm:[2,3,0,1] row_mask:0xf bank_mask:0xf bound_ctrl:1
	v_add_f32_dpp v65, v50, v50 quad_perm:[2,3,0,1] row_mask:0xf bank_mask:0xf bound_ctrl:1
	v_cndmask_b32_e64 v56, v64, v65, s[50:51]
	v_add_f32_dpp v64, v49, v49 quad_perm:[2,3,0,1] row_mask:0xf bank_mask:0xf bound_ctrl:1
	v_add_f32_dpp v65, v51, v51 quad_perm:[2,3,0,1] row_mask:0xf bank_mask:0xf bound_ctrl:1
	v_cndmask_b32_e64 v57, v64, v65, s[50:51]
	v_add_f32_dpp v64, v56, v56 quad_perm:[1,0,3,2] row_mask:0xf bank_mask:0xf bound_ctrl:1
	s_nop 0
	v_add_f32_dpp v65, v57, v57 quad_perm:[1,0,3,2] row_mask:0xf bank_mask:0xf bound_ctrl:1
	v_cndmask_b32_e64 v66, v64, v65, s[48:49]
	v_cvt_pk_bf16_f32 v66, v66, v66
	global_store_short v8, v66, s[12:13]
	s_add_u32 s12, s12, 0x8000
	s_addc_u32 s13, s13, 0
	s_branch .Lrw_next

.Lrw_skip_d1:
	ds_read_b64 v[84:85], v6 offset:12312
	ds_read_b128 v[86:89], v6 offset:12560
	ds_read_b128 v[90:93], v6 offset:12816
	ds_read_u16 v94, v7 offset:12304
	v_fma_mix_f32 v14, v10, v38, 0 op_sel:[0,0,0] op_sel_hi:[0,1,0]
	v_fma_mix_f32 v48, v10, v32, 0 op_sel:[0,0,0] op_sel_hi:[0,1,0]
	v_fma_mix_f32 v14, v11, v38, v14 op_sel:[0,1,0] op_sel_hi:[0,1,0]
	v_fma_mix_f32 v48, v11, v32, v48 op_sel:[0,1,0] op_sel_hi:[0,1,0]
	v_fma_mix_f32 v14, v12, v39, v14 op_sel:[0,0,0] op_sel_hi:[0,1,0]
	v_fma_mix_f32 v48, v12, v33, v48 op_sel:[0,0,0] op_sel_hi:[0,1,0]
	v_fma_mix_f32 v14, v13, v39, v14 op_sel:[0,1,0] op_sel_hi:[0,1,0]
	v_fma_mix_f32 v16, v10, v36, 0 op_sel:[0,0,0] op_sel_hi:[0,1,0]
	v_fma_mix_f32 v17, v11, v36, 0 op_sel:[0,1,0] op_sel_hi:[0,1,0]
	v_add_f32_dpp v20, v14, v14 quad_perm:[1,0,3,2] row_mask:0xf bank_mask:0xf bound_ctrl:1
	v_fma_mix_f32 v48, v13, v33, v48 op_sel:[0,1,0] op_sel_hi:[0,1,0]
	v_fma_mix_f32 v18, v12, v37, 0 op_sel:[0,0,0] op_sel_hi:[0,1,0]
	v_add_f32_dpp v20, v20, v20 quad_perm:[2,3,0,1] row_mask:0xf bank_mask:0xf bound_ctrl:1
	v_fma_mix_f32 v19, v13, v37, 0 op_sel:[0,1,0] op_sel_hi:[0,1,0]
	v_fma_mix_f32 v16, v46, v42, v16 op_sel:[0,0,0] op_sel_hi:[1,1,0]
	v_add_f32_dpp v20, v20, v20 row_half_mirror row_mask:0xf bank_mask:0xf bound_ctrl:1
	v_fma_mix_f32 v17, v46, v42, v17 op_sel:[0,1,0] op_sel_hi:[1,1,0]
	v_fma_mix_f32 v18, v46, v43, v18 op_sel:[0,0,0] op_sel_hi:[1,1,0]
	v_add_f32_dpp v20, v20, v20 row_mirror row_mask:0xf bank_mask:0xf bound_ctrl:1
	v_fma_mix_f32 v19, v46, v43, v19 op_sel:[0,1,0] op_sel_hi:[1,1,0]
	v_fma_mix_f32 v10, v20, v40, v16 op_sel:[0,0,0] op_sel_hi:[0,1,0]
	v_fma_mix_f32 v11, v20, v40, v17 op_sel:[0,1,0] op_sel_hi:[0,1,0]
	v_fma_mix_f32 v12, v20, v41, v18 op_sel:[0,0,0] op_sel_hi:[0,1,0]
	v_fma_mix_f32 v13, v20, v41, v19 op_sel:[0,1,0] op_sel_hi:[0,1,0]
	s_waitcnt lgkmcnt(4)
	ds_read_b64 v[24:25], v6 offset:11288
	ds_read_b128 v[26:29], v6 offset:11536
	ds_read_b128 v[30:33], v6 offset:11792
	ds_read_u16 v34, v7 offset:11280
	v_fma_mix_f32 v14, v10, v74, 0 op_sel:[0,0,0] op_sel_hi:[0,1,0]
	v_fma_mix_f32 v49, v10, v44, 0 op_sel:[0,0,0] op_sel_hi:[0,1,0]
	v_fma_mix_f32 v14, v11, v74, v14 op_sel:[0,1,0] op_sel_hi:[0,1,0]
	v_fma_mix_f32 v49, v11, v44, v49 op_sel:[0,1,0] op_sel_hi:[0,1,0]
	v_fma_mix_f32 v14, v12, v75, v14 op_sel:[0,0,0] op_sel_hi:[0,1,0]
	v_fma_mix_f32 v49, v12, v45, v49 op_sel:[0,0,0] op_sel_hi:[0,1,0]
	v_fma_mix_f32 v14, v13, v75, v14 op_sel:[0,1,0] op_sel_hi:[0,1,0]
	v_fma_mix_f32 v16, v10, v72, 0 op_sel:[0,0,0] op_sel_hi:[0,1,0]
	v_fma_mix_f32 v17, v11, v72, 0 op_sel:[0,1,0] op_sel_hi:[0,1,0]
	v_add_f32_dpp v20, v14, v14 quad_perm:[1,0,3,2] row_mask:0xf bank_mask:0xf bound_ctrl:1
	v_fma_mix_f32 v49, v13, v45, v49 op_sel:[0,1,0] op_sel_hi:[0,1,0]
	v_fma_mix_f32 v18, v12, v73, 0 op_sel:[0,0,0] op_sel_hi:[0,1,0]
	v_add_f32_dpp v20, v20, v20 quad_perm:[2,3,0,1] row_mask:0xf bank_mask:0xf bound_ctrl:1
	v_fma_mix_f32 v19, v13, v73, 0 op_sel:[0,1,0] op_sel_hi:[0,1,0]
	v_fma_mix_f32 v16, v82, v78, v16 op_sel:[0,0,0] op_sel_hi:[1,1,0]
	v_add_f32_dpp v20, v20, v20 row_half_mirror row_mask:0xf bank_mask:0xf bound_ctrl:1
	v_fma_mix_f32 v17, v82, v78, v17 op_sel:[0,1,0] op_sel_hi:[1,1,0]
	v_fma_mix_f32 v18, v82, v79, v18 op_sel:[0,0,0] op_sel_hi:[1,1,0]
	v_add_f32_dpp v20, v20, v20 row_mirror row_mask:0xf bank_mask:0xf bound_ctrl:1
	v_fma_mix_f32 v19, v82, v79, v19 op_sel:[0,1,0] op_sel_hi:[1,1,0]
	v_fma_mix_f32 v10, v20, v76, v16 op_sel:[0,0,0] op_sel_hi:[0,1,0]
	v_fma_mix_f32 v11, v20, v76, v17 op_sel:[0,1,0] op_sel_hi:[0,1,0]
	v_fma_mix_f32 v12, v20, v77, v18 op_sel:[0,0,0] op_sel_hi:[0,1,0]
	v_fma_mix_f32 v13, v20, v77, v19 op_sel:[0,1,0] op_sel_hi:[0,1,0]
	s_waitcnt lgkmcnt(4)
	ds_read_b64 v[36:37], v6 offset:10264
	ds_read_b128 v[38:41], v6 offset:10512
	ds_read_b128 v[42:45], v6 offset:10768
	ds_read_u16 v46, v7 offset:10256
	v_fma_mix_f32 v14, v10, v86, 0 op_sel:[0,0,0] op_sel_hi:[0,1,0]
	v_fma_mix_f32 v50, v10, v80, 0 op_sel:[0,0,0] op_sel_hi:[0,1,0]
	v_fma_mix_f32 v14, v11, v86, v14 op_sel:[0,1,0] op_sel_hi:[0,1,0]
	v_fma_mix_f32 v50, v11, v80, v50 op_sel:[0,1,0] op_sel_hi:[0,1,0]
	v_fma_mix_f32 v14, v12, v87, v14 op_sel:[0,0,0] op_sel_hi:[0,1,0]
	v_fma_mix_f32 v50, v12, v81, v50 op_sel:[0,0,0] op_sel_hi:[0,1,0]
	v_fma_mix_f32 v14, v13, v87, v14 op_sel:[0,1,0] op_sel_hi:[0,1,0]
	v_fma_mix_f32 v16, v10, v84, 0 op_sel:[0,0,0] op_sel_hi:[0,1,0]
	v_fma_mix_f32 v17, v11, v84, 0 op_sel:[0,1,0] op_sel_hi:[0,1,0]
	v_add_f32_dpp v20, v14, v14 quad_perm:[1,0,3,2] row_mask:0xf bank_mask:0xf bound_ctrl:1
	v_fma_mix_f32 v50, v13, v81, v50 op_sel:[0,1,0] op_sel_hi:[0,1,0]
	v_fma_mix_f32 v18, v12, v85, 0 op_sel:[0,0,0] op_sel_hi:[0,1,0]
	v_add_f32_dpp v20, v20, v20 quad_perm:[2,3,0,1] row_mask:0xf bank_mask:0xf bound_ctrl:1
	v_fma_mix_f32 v19, v13, v85, 0 op_sel:[0,1,0] op_sel_hi:[0,1,0]
	v_fma_mix_f32 v16, v94, v90, v16 op_sel:[0,0,0] op_sel_hi:[1,1,0]
	v_add_f32_dpp v20, v20, v20 row_half_mirror row_mask:0xf bank_mask:0xf bound_ctrl:1
	v_fma_mix_f32 v17, v94, v90, v17 op_sel:[0,1,0] op_sel_hi:[1,1,0]
	v_fma_mix_f32 v18, v94, v91, v18 op_sel:[0,0,0] op_sel_hi:[1,1,0]
	v_add_f32_dpp v20, v20, v20 row_mirror row_mask:0xf bank_mask:0xf bound_ctrl:1
	v_fma_mix_f32 v19, v94, v91, v19 op_sel:[0,1,0] op_sel_hi:[1,1,0]
	v_fma_mix_f32 v10, v20, v88, v16 op_sel:[0,0,0] op_sel_hi:[0,1,0]
	v_fma_mix_f32 v11, v20, v88, v17 op_sel:[0,1,0] op_sel_hi:[0,1,0]
	v_fma_mix_f32 v12, v20, v89, v18 op_sel:[0,0,0] op_sel_hi:[0,1,0]
	v_fma_mix_f32 v13, v20, v89, v19 op_sel:[0,1,0] op_sel_hi:[0,1,0]
	s_waitcnt lgkmcnt(4)
	ds_read_b64 v[72:73], v6 offset:9240
	ds_read_b128 v[74:77], v6 offset:9488
	ds_read_b128 v[78:81], v6 offset:9744
	ds_read_u16 v82, v7 offset:9232
	v_fma_mix_f32 v14, v10, v26, 0 op_sel:[0,0,0] op_sel_hi:[0,1,0]
	v_fma_mix_f32 v51, v10, v92, 0 op_sel:[0,0,0] op_sel_hi:[0,1,0]
	v_fma_mix_f32 v14, v11, v26, v14 op_sel:[0,1,0] op_sel_hi:[0,1,0]
	v_fma_mix_f32 v51, v11, v92, v51 op_sel:[0,1,0] op_sel_hi:[0,1,0]
	v_fma_mix_f32 v14, v12, v27, v14 op_sel:[0,0,0] op_sel_hi:[0,1,0]
	v_fma_mix_f32 v51, v12, v93, v51 op_sel:[0,0,0] op_sel_hi:[0,1,0]
	v_fma_mix_f32 v14, v13, v27, v14 op_sel:[0,1,0] op_sel_hi:[0,1,0]
	v_fma_mix_f32 v16, v10, v24, 0 op_sel:[0,0,0] op_sel_hi:[0,1,0]
	v_fma_mix_f32 v17, v11, v24, 0 op_sel:[0,1,0] op_sel_hi:[0,1,0]
	v_add_f32_dpp v20, v14, v14 quad_perm:[1,0,3,2] row_mask:0xf bank_mask:0xf bound_ctrl:1
	v_fma_mix_f32 v51, v13, v93, v51 op_sel:[0,1,0] op_sel_hi:[0,1,0]
	v_fma_mix_f32 v18, v12, v25, 0 op_sel:[0,0,0] op_sel_hi:[0,1,0]
	v_add_f32_dpp v20, v20, v20 quad_perm:[2,3,0,1] row_mask:0xf bank_mask:0xf bound_ctrl:1
	v_fma_mix_f32 v19, v13, v25, 0 op_sel:[0,1,0] op_sel_hi:[0,1,0]
	v_fma_mix_f32 v16, v34, v30, v16 op_sel:[0,0,0] op_sel_hi:[1,1,0]
	v_add_f32_dpp v20, v20, v20 row_half_mirror row_mask:0xf bank_mask:0xf bound_ctrl:1
	v_fma_mix_f32 v17, v34, v30, v17 op_sel:[0,1,0] op_sel_hi:[1,1,0]
	v_fma_mix_f32 v18, v34, v31, v18 op_sel:[0,0,0] op_sel_hi:[1,1,0]
	v_add_f32_dpp v20, v20, v20 row_mirror row_mask:0xf bank_mask:0xf bound_ctrl:1
	v_fma_mix_f32 v19, v34, v31, v19 op_sel:[0,1,0] op_sel_hi:[1,1,0]
	v_fma_mix_f32 v10, v20, v28, v16 op_sel:[0,0,0] op_sel_hi:[0,1,0]
	v_fma_mix_f32 v11, v20, v28, v17 op_sel:[0,1,0] op_sel_hi:[0,1,0]
	v_fma_mix_f32 v12, v20, v29, v18 op_sel:[0,0,0] op_sel_hi:[0,1,0]
	v_fma_mix_f32 v13, v20, v29, v19 op_sel:[0,1,0] op_sel_hi:[0,1,0]
	s_waitcnt lgkmcnt(4)
	ds_read_b64 v[84:85], v6 offset:8216
	ds_read_b128 v[86:89], v6 offset:8464
	ds_read_b128 v[90:93], v6 offset:8720
	ds_read_u16 v94, v7 offset:8208
	v_fma_mix_f32 v14, v10, v38, 0 op_sel:[0,0,0] op_sel_hi:[0,1,0]
	v_fma_mix_f32 v52, v10, v32, 0 op_sel:[0,0,0] op_sel_hi:[0,1,0]
	v_fma_mix_f32 v14, v11, v38, v14 op_sel:[0,1,0] op_sel_hi:[0,1,0]
	v_fma_mix_f32 v52, v11, v32, v52 op_sel:[0,1,0] op_sel_hi:[0,1,0]
	v_fma_mix_f32 v14, v12, v39, v14 op_sel:[0,0,0] op_sel_hi:[0,1,0]
	v_fma_mix_f32 v52, v12, v33, v52 op_sel:[0,0,0] op_sel_hi:[0,1,0]
	v_fma_mix_f32 v14, v13, v39, v14 op_sel:[0,1,0] op_sel_hi:[0,1,0]
	v_fma_mix_f32 v16, v10, v36, 0 op_sel:[0,0,0] op_sel_hi:[0,1,0]
	v_fma_mix_f32 v17, v11, v36, 0 op_sel:[0,1,0] op_sel_hi:[0,1,0]
	v_add_f32_dpp v20, v14, v14 quad_perm:[1,0,3,2] row_mask:0xf bank_mask:0xf bound_ctrl:1
	v_fma_mix_f32 v52, v13, v33, v52 op_sel:[0,1,0] op_sel_hi:[0,1,0]
	v_fma_mix_f32 v18, v12, v37, 0 op_sel:[0,0,0] op_sel_hi:[0,1,0]
	v_add_f32_dpp v20, v20, v20 quad_perm:[2,3,0,1] row_mask:0xf bank_mask:0xf bound_ctrl:1
	v_fma_mix_f32 v19, v13, v37, 0 op_sel:[0,1,0] op_sel_hi:[0,1,0]
	v_fma_mix_f32 v16, v46, v42, v16 op_sel:[0,0,0] op_sel_hi:[1,1,0]
	v_add_f32_dpp v20, v20, v20 row_half_mirror row_mask:0xf bank_mask:0xf bound_ctrl:1
	v_fma_mix_f32 v17, v46, v42, v17 op_sel:[0,1,0] op_sel_hi:[1,1,0]
	v_fma_mix_f32 v18, v46, v43, v18 op_sel:[0,0,0] op_sel_hi:[1,1,0]
	v_add_f32_dpp v20, v20, v20 row_mirror row_mask:0xf bank_mask:0xf bound_ctrl:1
	v_fma_mix_f32 v19, v46, v43, v19 op_sel:[0,1,0] op_sel_hi:[1,1,0]
	v_fma_mix_f32 v10, v20, v40, v16 op_sel:[0,0,0] op_sel_hi:[0,1,0]
	v_fma_mix_f32 v11, v20, v40, v17 op_sel:[0,1,0] op_sel_hi:[0,1,0]
	v_fma_mix_f32 v12, v20, v41, v18 op_sel:[0,0,0] op_sel_hi:[0,1,0]
	v_fma_mix_f32 v13, v20, v41, v19 op_sel:[0,1,0] op_sel_hi:[0,1,0]
	s_waitcnt lgkmcnt(4)
	ds_read_b64 v[24:25], v6 offset:7192
	ds_read_b128 v[26:29], v6 offset:7440
	ds_read_b128 v[30:33], v6 offset:7696
	ds_read_u16 v34, v7 offset:7184
	v_fma_mix_f32 v14, v10, v74, 0 op_sel:[0,0,0] op_sel_hi:[0,1,0]
	v_fma_mix_f32 v53, v10, v44, 0 op_sel:[0,0,0] op_sel_hi:[0,1,0]
	v_fma_mix_f32 v14, v11, v74, v14 op_sel:[0,1,0] op_sel_hi:[0,1,0]
	v_fma_mix_f32 v53, v11, v44, v53 op_sel:[0,1,0] op_sel_hi:[0,1,0]
	v_fma_mix_f32 v14, v12, v75, v14 op_sel:[0,0,0] op_sel_hi:[0,1,0]
	v_fma_mix_f32 v53, v12, v45, v53 op_sel:[0,0,0] op_sel_hi:[0,1,0]
	v_fma_mix_f32 v14, v13, v75, v14 op_sel:[0,1,0] op_sel_hi:[0,1,0]
	v_fma_mix_f32 v16, v10, v72, 0 op_sel:[0,0,0] op_sel_hi:[0,1,0]
	v_fma_mix_f32 v17, v11, v72, 0 op_sel:[0,1,0] op_sel_hi:[0,1,0]
	v_add_f32_dpp v20, v14, v14 quad_perm:[1,0,3,2] row_mask:0xf bank_mask:0xf bound_ctrl:1
	v_fma_mix_f32 v53, v13, v45, v53 op_sel:[0,1,0] op_sel_hi:[0,1,0]
	v_fma_mix_f32 v18, v12, v73, 0 op_sel:[0,0,0] op_sel_hi:[0,1,0]
	v_add_f32_dpp v20, v20, v20 quad_perm:[2,3,0,1] row_mask:0xf bank_mask:0xf bound_ctrl:1
	v_fma_mix_f32 v19, v13, v73, 0 op_sel:[0,1,0] op_sel_hi:[0,1,0]
	v_fma_mix_f32 v16, v82, v78, v16 op_sel:[0,0,0] op_sel_hi:[1,1,0]
	v_add_f32_dpp v20, v20, v20 row_half_mirror row_mask:0xf bank_mask:0xf bound_ctrl:1
	v_fma_mix_f32 v17, v82, v78, v17 op_sel:[0,1,0] op_sel_hi:[1,1,0]
	v_fma_mix_f32 v18, v82, v79, v18 op_sel:[0,0,0] op_sel_hi:[1,1,0]
	v_add_f32_dpp v20, v20, v20 row_mirror row_mask:0xf bank_mask:0xf bound_ctrl:1
	v_fma_mix_f32 v19, v82, v79, v19 op_sel:[0,1,0] op_sel_hi:[1,1,0]
	v_fma_mix_f32 v10, v20, v76, v16 op_sel:[0,0,0] op_sel_hi:[0,1,0]
	v_fma_mix_f32 v11, v20, v76, v17 op_sel:[0,1,0] op_sel_hi:[0,1,0]
	v_fma_mix_f32 v12, v20, v77, v18 op_sel:[0,0,0] op_sel_hi:[0,1,0]
	v_fma_mix_f32 v13, v20, v77, v19 op_sel:[0,1,0] op_sel_hi:[0,1,0]
	s_waitcnt lgkmcnt(4)
	ds_read_b64 v[36:37], v6 offset:6168
	ds_read_b128 v[38:41], v6 offset:6416
	ds_read_b128 v[42:45], v6 offset:6672
	ds_read_u16 v46, v7 offset:6160
	v_fma_mix_f32 v14, v10, v86, 0 op_sel:[0,0,0] op_sel_hi:[0,1,0]
	v_fma_mix_f32 v54, v10, v80, 0 op_sel:[0,0,0] op_sel_hi:[0,1,0]
	v_fma_mix_f32 v14, v11, v86, v14 op_sel:[0,1,0] op_sel_hi:[0,1,0]
	v_fma_mix_f32 v54, v11, v80, v54 op_sel:[0,1,0] op_sel_hi:[0,1,0]
	v_fma_mix_f32 v14, v12, v87, v14 op_sel:[0,0,0] op_sel_hi:[0,1,0]
	v_fma_mix_f32 v54, v12, v81, v54 op_sel:[0,0,0] op_sel_hi:[0,1,0]
	v_fma_mix_f32 v14, v13, v87, v14 op_sel:[0,1,0] op_sel_hi:[0,1,0]
	v_fma_mix_f32 v16, v10, v84, 0 op_sel:[0,0,0] op_sel_hi:[0,1,0]
	v_fma_mix_f32 v17, v11, v84, 0 op_sel:[0,1,0] op_sel_hi:[0,1,0]
	v_add_f32_dpp v20, v14, v14 quad_perm:[1,0,3,2] row_mask:0xf bank_mask:0xf bound_ctrl:1
	v_fma_mix_f32 v54, v13, v81, v54 op_sel:[0,1,0] op_sel_hi:[0,1,0]
	v_fma_mix_f32 v18, v12, v85, 0 op_sel:[0,0,0] op_sel_hi:[0,1,0]
	v_add_f32_dpp v20, v20, v20 quad_perm:[2,3,0,1] row_mask:0xf bank_mask:0xf bound_ctrl:1
	v_fma_mix_f32 v19, v13, v85, 0 op_sel:[0,1,0] op_sel_hi:[0,1,0]
	v_fma_mix_f32 v16, v94, v90, v16 op_sel:[0,0,0] op_sel_hi:[1,1,0]
	v_add_f32_dpp v20, v20, v20 row_half_mirror row_mask:0xf bank_mask:0xf bound_ctrl:1
	v_fma_mix_f32 v17, v94, v90, v17 op_sel:[0,1,0] op_sel_hi:[1,1,0]
	v_fma_mix_f32 v18, v94, v91, v18 op_sel:[0,0,0] op_sel_hi:[1,1,0]
	v_add_f32_dpp v20, v20, v20 row_mirror row_mask:0xf bank_mask:0xf bound_ctrl:1
	v_fma_mix_f32 v19, v94, v91, v19 op_sel:[0,1,0] op_sel_hi:[1,1,0]
	v_fma_mix_f32 v10, v20, v88, v16 op_sel:[0,0,0] op_sel_hi:[0,1,0]
	v_fma_mix_f32 v11, v20, v88, v17 op_sel:[0,1,0] op_sel_hi:[0,1,0]
	v_fma_mix_f32 v12, v20, v89, v18 op_sel:[0,0,0] op_sel_hi:[0,1,0]
	v_fma_mix_f32 v13, v20, v89, v19 op_sel:[0,1,0] op_sel_hi:[0,1,0]
	s_waitcnt lgkmcnt(4)
	ds_read_b64 v[72:73], v6 offset:5144
	ds_read_b128 v[74:77], v6 offset:5392
	ds_read_b128 v[78:81], v6 offset:5648
	ds_read_u16 v82, v7 offset:5136
	v_fma_mix_f32 v14, v10, v26, 0 op_sel:[0,0,0] op_sel_hi:[0,1,0]
	v_fma_mix_f32 v55, v10, v92, 0 op_sel:[0,0,0] op_sel_hi:[0,1,0]
	v_fma_mix_f32 v14, v11, v26, v14 op_sel:[0,1,0] op_sel_hi:[0,1,0]
	v_fma_mix_f32 v55, v11, v92, v55 op_sel:[0,1,0] op_sel_hi:[0,1,0]
	v_fma_mix_f32 v14, v12, v27, v14 op_sel:[0,0,0] op_sel_hi:[0,1,0]
	v_fma_mix_f32 v55, v12, v93, v55 op_sel:[0,0,0] op_sel_hi:[0,1,0]
	v_fma_mix_f32 v14, v13, v27, v14 op_sel:[0,1,0] op_sel_hi:[0,1,0]
	v_fma_mix_f32 v16, v10, v24, 0 op_sel:[0,0,0] op_sel_hi:[0,1,0]
	v_fma_mix_f32 v17, v11, v24, 0 op_sel:[0,1,0] op_sel_hi:[0,1,0]
	v_add_f32_dpp v20, v14, v14 quad_perm:[1,0,3,2] row_mask:0xf bank_mask:0xf bound_ctrl:1
	v_fma_mix_f32 v55, v13, v93, v55 op_sel:[0,1,0] op_sel_hi:[0,1,0]
	v_fma_mix_f32 v18, v12, v25, 0 op_sel:[0,0,0] op_sel_hi:[0,1,0]
	v_add_f32_dpp v20, v20, v20 quad_perm:[2,3,0,1] row_mask:0xf bank_mask:0xf bound_ctrl:1
	v_fma_mix_f32 v19, v13, v25, 0 op_sel:[0,1,0] op_sel_hi:[0,1,0]
	v_fma_mix_f32 v16, v34, v30, v16 op_sel:[0,0,0] op_sel_hi:[1,1,0]
	v_add_f32_dpp v20, v20, v20 row_half_mirror row_mask:0xf bank_mask:0xf bound_ctrl:1
	v_fma_mix_f32 v17, v34, v30, v17 op_sel:[0,1,0] op_sel_hi:[1,1,0]
	v_fma_mix_f32 v18, v34, v31, v18 op_sel:[0,0,0] op_sel_hi:[1,1,0]
	v_add_f32_dpp v20, v20, v20 row_mirror row_mask:0xf bank_mask:0xf bound_ctrl:1
	v_fma_mix_f32 v19, v34, v31, v19 op_sel:[0,1,0] op_sel_hi:[1,1,0]
	v_fma_mix_f32 v10, v20, v28, v16 op_sel:[0,0,0] op_sel_hi:[0,1,0]
	v_fma_mix_f32 v11, v20, v28, v17 op_sel:[0,1,0] op_sel_hi:[0,1,0]
	v_fma_mix_f32 v12, v20, v29, v18 op_sel:[0,0,0] op_sel_hi:[0,1,0]
	v_fma_mix_f32 v13, v20, v29, v19 op_sel:[0,1,0] op_sel_hi:[0,1,0]
	s_waitcnt lgkmcnt(4)
	ds_read_b64 v[84:85], v6 offset:4120
	ds_read_b128 v[86:89], v6 offset:4368
	ds_read_b128 v[90:93], v6 offset:4624
	ds_read_u16 v94, v7 offset:4112
	v_fma_mix_f32 v14, v10, v38, 0 op_sel:[0,0,0] op_sel_hi:[0,1,0]
	v_fma_mix_f32 v56, v10, v32, 0 op_sel:[0,0,0] op_sel_hi:[0,1,0]
	v_fma_mix_f32 v14, v11, v38, v14 op_sel:[0,1,0] op_sel_hi:[0,1,0]
	v_fma_mix_f32 v56, v11, v32, v56 op_sel:[0,1,0] op_sel_hi:[0,1,0]
	v_fma_mix_f32 v14, v12, v39, v14 op_sel:[0,0,0] op_sel_hi:[0,1,0]
	v_fma_mix_f32 v56, v12, v33, v56 op_sel:[0,0,0] op_sel_hi:[0,1,0]
	v_fma_mix_f32 v14, v13, v39, v14 op_sel:[0,1,0] op_sel_hi:[0,1,0]
	v_fma_mix_f32 v16, v10, v36, 0 op_sel:[0,0,0] op_sel_hi:[0,1,0]
	v_fma_mix_f32 v17, v11, v36, 0 op_sel:[0,1,0] op_sel_hi:[0,1,0]
	v_add_f32_dpp v20, v14, v14 quad_perm:[1,0,3,2] row_mask:0xf bank_mask:0xf bound_ctrl:1
	v_fma_mix_f32 v56, v13, v33, v56 op_sel:[0,1,0] op_sel_hi:[0,1,0]
	v_fma_mix_f32 v18, v12, v37, 0 op_sel:[0,0,0] op_sel_hi:[0,1,0]
	v_add_f32_dpp v20, v20, v20 quad_perm:[2,3,0,1] row_mask:0xf bank_mask:0xf bound_ctrl:1
	v_fma_mix_f32 v19, v13, v37, 0 op_sel:[0,1,0] op_sel_hi:[0,1,0]
	v_fma_mix_f32 v16, v46, v42, v16 op_sel:[0,0,0] op_sel_hi:[1,1,0]
	v_add_f32_dpp v20, v20, v20 row_half_mirror row_mask:0xf bank_mask:0xf bound_ctrl:1
	v_fma_mix_f32 v17, v46, v42, v17 op_sel:[0,1,0] op_sel_hi:[1,1,0]
	v_fma_mix_f32 v18, v46, v43, v18 op_sel:[0,0,0] op_sel_hi:[1,1,0]
	v_add_f32_dpp v20, v20, v20 row_mirror row_mask:0xf bank_mask:0xf bound_ctrl:1
	v_fma_mix_f32 v19, v46, v43, v19 op_sel:[0,1,0] op_sel_hi:[1,1,0]
	v_fma_mix_f32 v10, v20, v40, v16 op_sel:[0,0,0] op_sel_hi:[0,1,0]
	v_fma_mix_f32 v11, v20, v40, v17 op_sel:[0,1,0] op_sel_hi:[0,1,0]
	v_fma_mix_f32 v12, v20, v41, v18 op_sel:[0,0,0] op_sel_hi:[0,1,0]
	v_fma_mix_f32 v13, v20, v41, v19 op_sel:[0,1,0] op_sel_hi:[0,1,0]
	s_waitcnt lgkmcnt(4)
	ds_read_b64 v[24:25], v6 offset:3096
	ds_read_b128 v[26:29], v6 offset:3344
	ds_read_b128 v[30:33], v6 offset:3600
	ds_read_u16 v34, v7 offset:3088
	v_fma_mix_f32 v14, v10, v74, 0 op_sel:[0,0,0] op_sel_hi:[0,1,0]
	v_fma_mix_f32 v57, v10, v44, 0 op_sel:[0,0,0] op_sel_hi:[0,1,0]
	v_fma_mix_f32 v14, v11, v74, v14 op_sel:[0,1,0] op_sel_hi:[0,1,0]
	v_fma_mix_f32 v57, v11, v44, v57 op_sel:[0,1,0] op_sel_hi:[0,1,0]
	v_fma_mix_f32 v14, v12, v75, v14 op_sel:[0,0,0] op_sel_hi:[0,1,0]
	v_fma_mix_f32 v57, v12, v45, v57 op_sel:[0,0,0] op_sel_hi:[0,1,0]
	v_fma_mix_f32 v14, v13, v75, v14 op_sel:[0,1,0] op_sel_hi:[0,1,0]
	v_fma_mix_f32 v16, v10, v72, 0 op_sel:[0,0,0] op_sel_hi:[0,1,0]
	v_fma_mix_f32 v17, v11, v72, 0 op_sel:[0,1,0] op_sel_hi:[0,1,0]
	v_add_f32_dpp v20, v14, v14 quad_perm:[1,0,3,2] row_mask:0xf bank_mask:0xf bound_ctrl:1
	v_fma_mix_f32 v57, v13, v45, v57 op_sel:[0,1,0] op_sel_hi:[0,1,0]
	v_fma_mix_f32 v18, v12, v73, 0 op_sel:[0,0,0] op_sel_hi:[0,1,0]
	v_add_f32_dpp v20, v20, v20 quad_perm:[2,3,0,1] row_mask:0xf bank_mask:0xf bound_ctrl:1
	v_fma_mix_f32 v19, v13, v73, 0 op_sel:[0,1,0] op_sel_hi:[0,1,0]
	v_fma_mix_f32 v16, v82, v78, v16 op_sel:[0,0,0] op_sel_hi:[1,1,0]
	v_add_f32_dpp v20, v20, v20 row_half_mirror row_mask:0xf bank_mask:0xf bound_ctrl:1
	v_fma_mix_f32 v17, v82, v78, v17 op_sel:[0,1,0] op_sel_hi:[1,1,0]
	v_fma_mix_f32 v18, v82, v79, v18 op_sel:[0,0,0] op_sel_hi:[1,1,0]
	v_add_f32_dpp v20, v20, v20 row_mirror row_mask:0xf bank_mask:0xf bound_ctrl:1
	v_fma_mix_f32 v19, v82, v79, v19 op_sel:[0,1,0] op_sel_hi:[1,1,0]
	v_fma_mix_f32 v10, v20, v76, v16 op_sel:[0,0,0] op_sel_hi:[0,1,0]
	v_fma_mix_f32 v11, v20, v76, v17 op_sel:[0,1,0] op_sel_hi:[0,1,0]
	v_fma_mix_f32 v12, v20, v77, v18 op_sel:[0,0,0] op_sel_hi:[0,1,0]
	v_fma_mix_f32 v13, v20, v77, v19 op_sel:[0,1,0] op_sel_hi:[0,1,0]
	s_waitcnt lgkmcnt(4)
	ds_read_b64 v[36:37], v6 offset:2072
	ds_read_b128 v[38:41], v6 offset:2320
	ds_read_b128 v[42:45], v6 offset:2576
	ds_read_u16 v46, v7 offset:2064
	v_fma_mix_f32 v14, v10, v86, 0 op_sel:[0,0,0] op_sel_hi:[0,1,0]
	v_fma_mix_f32 v58, v10, v80, 0 op_sel:[0,0,0] op_sel_hi:[0,1,0]
	v_fma_mix_f32 v14, v11, v86, v14 op_sel:[0,1,0] op_sel_hi:[0,1,0]
	v_fma_mix_f32 v58, v11, v80, v58 op_sel:[0,1,0] op_sel_hi:[0,1,0]
	v_fma_mix_f32 v14, v12, v87, v14 op_sel:[0,0,0] op_sel_hi:[0,1,0]
	v_fma_mix_f32 v58, v12, v81, v58 op_sel:[0,0,0] op_sel_hi:[0,1,0]
	v_fma_mix_f32 v14, v13, v87, v14 op_sel:[0,1,0] op_sel_hi:[0,1,0]
	v_fma_mix_f32 v16, v10, v84, 0 op_sel:[0,0,0] op_sel_hi:[0,1,0]
	v_fma_mix_f32 v17, v11, v84, 0 op_sel:[0,1,0] op_sel_hi:[0,1,0]
	v_add_f32_dpp v20, v14, v14 quad_perm:[1,0,3,2] row_mask:0xf bank_mask:0xf bound_ctrl:1
	v_fma_mix_f32 v58, v13, v81, v58 op_sel:[0,1,0] op_sel_hi:[0,1,0]
	v_fma_mix_f32 v18, v12, v85, 0 op_sel:[0,0,0] op_sel_hi:[0,1,0]
	v_add_f32_dpp v20, v20, v20 quad_perm:[2,3,0,1] row_mask:0xf bank_mask:0xf bound_ctrl:1
	v_fma_mix_f32 v19, v13, v85, 0 op_sel:[0,1,0] op_sel_hi:[0,1,0]
	v_fma_mix_f32 v16, v94, v90, v16 op_sel:[0,0,0] op_sel_hi:[1,1,0]
	v_add_f32_dpp v20, v20, v20 row_half_mirror row_mask:0xf bank_mask:0xf bound_ctrl:1
	v_fma_mix_f32 v17, v94, v90, v17 op_sel:[0,1,0] op_sel_hi:[1,1,0]
	v_fma_mix_f32 v18, v94, v91, v18 op_sel:[0,0,0] op_sel_hi:[1,1,0]
	v_add_f32_dpp v20, v20, v20 row_mirror row_mask:0xf bank_mask:0xf bound_ctrl:1
	v_fma_mix_f32 v19, v94, v91, v19 op_sel:[0,1,0] op_sel_hi:[1,1,0]
	v_fma_mix_f32 v10, v20, v88, v16 op_sel:[0,0,0] op_sel_hi:[0,1,0]
	v_fma_mix_f32 v11, v20, v88, v17 op_sel:[0,1,0] op_sel_hi:[0,1,0]
	v_fma_mix_f32 v12, v20, v89, v18 op_sel:[0,0,0] op_sel_hi:[0,1,0]
	v_fma_mix_f32 v13, v20, v89, v19 op_sel:[0,1,0] op_sel_hi:[0,1,0]
	s_waitcnt lgkmcnt(4)
	ds_read_b64 v[72:73], v6 offset:1048
	ds_read_b128 v[74:77], v6 offset:1296
	ds_read_b128 v[78:81], v6 offset:1552
	ds_read_u16 v82, v7 offset:1040
	v_fma_mix_f32 v14, v10, v26, 0 op_sel:[0,0,0] op_sel_hi:[0,1,0]
	v_fma_mix_f32 v59, v10, v92, 0 op_sel:[0,0,0] op_sel_hi:[0,1,0]
	v_fma_mix_f32 v14, v11, v26, v14 op_sel:[0,1,0] op_sel_hi:[0,1,0]
	v_fma_mix_f32 v59, v11, v92, v59 op_sel:[0,1,0] op_sel_hi:[0,1,0]
	v_fma_mix_f32 v14, v12, v27, v14 op_sel:[0,0,0] op_sel_hi:[0,1,0]
	v_fma_mix_f32 v59, v12, v93, v59 op_sel:[0,0,0] op_sel_hi:[0,1,0]
	v_fma_mix_f32 v14, v13, v27, v14 op_sel:[0,1,0] op_sel_hi:[0,1,0]
	v_fma_mix_f32 v16, v10, v24, 0 op_sel:[0,0,0] op_sel_hi:[0,1,0]
	v_fma_mix_f32 v17, v11, v24, 0 op_sel:[0,1,0] op_sel_hi:[0,1,0]
	v_add_f32_dpp v20, v14, v14 quad_perm:[1,0,3,2] row_mask:0xf bank_mask:0xf bound_ctrl:1
	v_fma_mix_f32 v59, v13, v93, v59 op_sel:[0,1,0] op_sel_hi:[0,1,0]
	v_fma_mix_f32 v18, v12, v25, 0 op_sel:[0,0,0] op_sel_hi:[0,1,0]
	v_add_f32_dpp v20, v20, v20 quad_perm:[2,3,0,1] row_mask:0xf bank_mask:0xf bound_ctrl:1
	v_fma_mix_f32 v19, v13, v25, 0 op_sel:[0,1,0] op_sel_hi:[0,1,0]
	v_fma_mix_f32 v16, v34, v30, v16 op_sel:[0,0,0] op_sel_hi:[1,1,0]
	v_add_f32_dpp v20, v20, v20 row_half_mirror row_mask:0xf bank_mask:0xf bound_ctrl:1
	v_fma_mix_f32 v17, v34, v30, v17 op_sel:[0,1,0] op_sel_hi:[1,1,0]
	v_fma_mix_f32 v18, v34, v31, v18 op_sel:[0,0,0] op_sel_hi:[1,1,0]
	v_add_f32_dpp v20, v20, v20 row_mirror row_mask:0xf bank_mask:0xf bound_ctrl:1
	v_fma_mix_f32 v19, v34, v31, v19 op_sel:[0,1,0] op_sel_hi:[1,1,0]
	v_fma_mix_f32 v10, v20, v28, v16 op_sel:[0,0,0] op_sel_hi:[0,1,0]
	v_fma_mix_f32 v11, v20, v28, v17 op_sel:[0,1,0] op_sel_hi:[0,1,0]
	v_fma_mix_f32 v12, v20, v29, v18 op_sel:[0,0,0] op_sel_hi:[0,1,0]
	v_fma_mix_f32 v13, v20, v29, v19 op_sel:[0,1,0] op_sel_hi:[0,1,0]
	s_waitcnt lgkmcnt(4)
	ds_read_b128 v[100:103], v9
	ds_read_b128 v[104:107], v9 offset:16
	ds_read_b64 v[84:85], v6 offset:24
	ds_read_b128 v[86:89], v6 offset:272
	ds_read_b128 v[90:93], v6 offset:528
	ds_read_u16 v94, v7 offset:16
	v_fma_mix_f32 v14, v10, v38, 0 op_sel:[0,0,0] op_sel_hi:[0,1,0]
	v_fma_mix_f32 v60, v10, v32, 0 op_sel:[0,0,0] op_sel_hi:[0,1,0]
	v_fma_mix_f32 v14, v11, v38, v14 op_sel:[0,1,0] op_sel_hi:[0,1,0]
	v_fma_mix_f32 v60, v11, v32, v60 op_sel:[0,1,0] op_sel_hi:[0,1,0]
	v_fma_mix_f32 v14, v12, v39, v14 op_sel:[0,0,0] op_sel_hi:[0,1,0]
	v_fma_mix_f32 v60, v12, v33, v60 op_sel:[0,0,0] op_sel_hi:[0,1,0]
	v_fma_mix_f32 v14, v13, v39, v14 op_sel:[0,1,0] op_sel_hi:[0,1,0]
	v_fma_mix_f32 v16, v10, v36, 0 op_sel:[0,0,0] op_sel_hi:[0,1,0]
	v_fma_mix_f32 v17, v11, v36, 0 op_sel:[0,1,0] op_sel_hi:[0,1,0]
	v_add_f32_dpp v20, v14, v14 quad_perm:[1,0,3,2] row_mask:0xf bank_mask:0xf bound_ctrl:1
	v_fma_mix_f32 v60, v13, v33, v60 op_sel:[0,1,0] op_sel_hi:[0,1,0]
	v_fma_mix_f32 v18, v12, v37, 0 op_sel:[0,0,0] op_sel_hi:[0,1,0]
	v_add_f32_dpp v20, v20, v20 quad_perm:[2,3,0,1] row_mask:0xf bank_mask:0xf bound_ctrl:1
	v_fma_mix_f32 v19, v13, v37, 0 op_sel:[0,1,0] op_sel_hi:[0,1,0]
	v_fma_mix_f32 v16, v46, v42, v16 op_sel:[0,0,0] op_sel_hi:[1,1,0]
	v_add_f32_dpp v20, v20, v20 row_half_mirror row_mask:0xf bank_mask:0xf bound_ctrl:1
	v_fma_mix_f32 v17, v46, v42, v17 op_sel:[0,1,0] op_sel_hi:[1,1,0]
	v_fma_mix_f32 v18, v46, v43, v18 op_sel:[0,0,0] op_sel_hi:[1,1,0]
	v_add_f32_dpp v20, v20, v20 row_mirror row_mask:0xf bank_mask:0xf bound_ctrl:1
	v_fma_mix_f32 v19, v46, v43, v19 op_sel:[0,1,0] op_sel_hi:[1,1,0]
	v_fma_mix_f32 v10, v20, v40, v16 op_sel:[0,0,0] op_sel_hi:[0,1,0]
	v_fma_mix_f32 v11, v20, v40, v17 op_sel:[0,1,0] op_sel_hi:[0,1,0]
	v_fma_mix_f32 v12, v20, v41, v18 op_sel:[0,0,0] op_sel_hi:[0,1,0]
	v_fma_mix_f32 v13, v20, v41, v19 op_sel:[0,1,0] op_sel_hi:[0,1,0]
	s_waitcnt lgkmcnt(4)
	v_add_u32_e32 v6, 0xffffc000, v6
	v_add_u32_e32 v7, 0xffffc000, v7
	v_and_b32_e32 v6, 0x1ffff, v6
	v_and_b32_e32 v7, 0x1ffff, v7
	ds_read_b64 v[24:25], v6 offset:15384
	ds_read_b128 v[26:29], v6 offset:15632
	ds_read_b128 v[30:33], v6 offset:15888
	ds_read_u16 v34, v7 offset:15376
	v_fma_mix_f32 v14, v10, v74, 0 op_sel:[0,0,0] op_sel_hi:[0,1,0]
	v_fma_mix_f32 v61, v10, v44, 0 op_sel:[0,0,0] op_sel_hi:[0,1,0]
	v_fma_mix_f32 v14, v11, v74, v14 op_sel:[0,1,0] op_sel_hi:[0,1,0]
	v_fma_mix_f32 v61, v11, v44, v61 op_sel:[0,1,0] op_sel_hi:[0,1,0]
	v_fma_mix_f32 v14, v12, v75, v14 op_sel:[0,0,0] op_sel_hi:[0,1,0]
	v_fma_mix_f32 v61, v12, v45, v61 op_sel:[0,0,0] op_sel_hi:[0,1,0]
	v_fma_mix_f32 v14, v13, v75, v14 op_sel:[0,1,0] op_sel_hi:[0,1,0]
	v_fma_mix_f32 v16, v10, v72, 0 op_sel:[0,0,0] op_sel_hi:[0,1,0]
	v_fma_mix_f32 v17, v11, v72, 0 op_sel:[0,1,0] op_sel_hi:[0,1,0]
	v_add_f32_dpp v20, v14, v14 quad_perm:[1,0,3,2] row_mask:0xf bank_mask:0xf bound_ctrl:1
	v_fma_mix_f32 v61, v13, v45, v61 op_sel:[0,1,0] op_sel_hi:[0,1,0]
	v_fma_mix_f32 v18, v12, v73, 0 op_sel:[0,0,0] op_sel_hi:[0,1,0]
	v_add_f32_dpp v20, v20, v20 quad_perm:[2,3,0,1] row_mask:0xf bank_mask:0xf bound_ctrl:1
	v_fma_mix_f32 v19, v13, v73, 0 op_sel:[0,1,0] op_sel_hi:[0,1,0]
	v_fma_mix_f32 v16, v82, v78, v16 op_sel:[0,0,0] op_sel_hi:[1,1,0]
	v_add_f32_dpp v20, v20, v20 row_half_mirror row_mask:0xf bank_mask:0xf bound_ctrl:1
	v_fma_mix_f32 v17, v82, v78, v17 op_sel:[0,1,0] op_sel_hi:[1,1,0]
	v_fma_mix_f32 v18, v82, v79, v18 op_sel:[0,0,0] op_sel_hi:[1,1,0]
	v_add_f32_dpp v20, v20, v20 row_mirror row_mask:0xf bank_mask:0xf bound_ctrl:1
	v_fma_mix_f32 v19, v82, v79, v19 op_sel:[0,1,0] op_sel_hi:[1,1,0]
	v_fma_mix_f32 v10, v20, v76, v16 op_sel:[0,0,0] op_sel_hi:[0,1,0]
	v_fma_mix_f32 v11, v20, v76, v17 op_sel:[0,1,0] op_sel_hi:[0,1,0]
	v_fma_mix_f32 v12, v20, v77, v18 op_sel:[0,0,0] op_sel_hi:[0,1,0]
	v_fma_mix_f32 v13, v20, v77, v19 op_sel:[0,1,0] op_sel_hi:[0,1,0]
	s_waitcnt lgkmcnt(4)
	ds_read_b64 v[36:37], v6 offset:14360
	ds_read_b128 v[38:41], v6 offset:14608
	ds_read_b128 v[42:45], v6 offset:14864
	ds_read_u16 v46, v7 offset:14352
	v_fma_mix_f32 v14, v10, v86, 0 op_sel:[0,0,0] op_sel_hi:[0,1,0]
	v_fma_mix_f32 v62, v10, v80, 0 op_sel:[0,0,0] op_sel_hi:[0,1,0]
	v_fma_mix_f32 v14, v11, v86, v14 op_sel:[0,1,0] op_sel_hi:[0,1,0]
	v_fma_mix_f32 v62, v11, v80, v62 op_sel:[0,1,0] op_sel_hi:[0,1,0]
	v_fma_mix_f32 v14, v12, v87, v14 op_sel:[0,0,0] op_sel_hi:[0,1,0]
	v_fma_mix_f32 v62, v12, v81, v62 op_sel:[0,0,0] op_sel_hi:[0,1,0]
	v_fma_mix_f32 v14, v13, v87, v14 op_sel:[0,1,0] op_sel_hi:[0,1,0]
	v_fma_mix_f32 v16, v10, v84, 0 op_sel:[0,0,0] op_sel_hi:[0,1,0]
	v_fma_mix_f32 v17, v11, v84, 0 op_sel:[0,1,0] op_sel_hi:[0,1,0]
	v_add_f32_dpp v20, v14, v14 quad_perm:[1,0,3,2] row_mask:0xf bank_mask:0xf bound_ctrl:1
	v_fma_mix_f32 v62, v13, v81, v62 op_sel:[0,1,0] op_sel_hi:[0,1,0]
	v_fma_mix_f32 v18, v12, v85, 0 op_sel:[0,0,0] op_sel_hi:[0,1,0]
	v_add_f32_dpp v20, v20, v20 quad_perm:[2,3,0,1] row_mask:0xf bank_mask:0xf bound_ctrl:1
	v_fma_mix_f32 v19, v13, v85, 0 op_sel:[0,1,0] op_sel_hi:[0,1,0]
	v_fma_mix_f32 v16, v94, v90, v16 op_sel:[0,0,0] op_sel_hi:[1,1,0]
	v_add_f32_dpp v20, v20, v20 row_half_mirror row_mask:0xf bank_mask:0xf bound_ctrl:1
	v_fma_mix_f32 v17, v94, v90, v17 op_sel:[0,1,0] op_sel_hi:[1,1,0]
	v_fma_mix_f32 v18, v94, v91, v18 op_sel:[0,0,0] op_sel_hi:[1,1,0]
	v_add_f32_dpp v20, v20, v20 row_mirror row_mask:0xf bank_mask:0xf bound_ctrl:1
	v_fma_mix_f32 v19, v94, v91, v19 op_sel:[0,1,0] op_sel_hi:[1,1,0]
	v_fma_mix_f32 v10, v20, v88, v16 op_sel:[0,0,0] op_sel_hi:[0,1,0]
	v_fma_mix_f32 v11, v20, v88, v17 op_sel:[0,1,0] op_sel_hi:[0,1,0]
	v_fma_mix_f32 v12, v20, v89, v18 op_sel:[0,0,0] op_sel_hi:[0,1,0]
	v_fma_mix_f32 v13, v20, v89, v19 op_sel:[0,1,0] op_sel_hi:[0,1,0]
	s_waitcnt lgkmcnt(4)
	s_add_u32 s15, s15, 1
	s_add_u32 s14, s14, 1
	v_mov_b32_e32 v69, s15
	ds_write_b32 v68, v69
	s_cmp_lt_u32 s14, 0x100
	s_cbranch_scc1 .Lrw_blk_d1
; DEVINL u16 f2bf(float a) { return (u16)(pk2(a, 0.f) & 0xffffu); }
; #define RW_STEP2(B) RW_STEP(B, WvA, XA, KrA, vhA, WvB, XB, KrB, vhB); RW_STEP((B) + 1, WvB, XB, KrB, vhB, WvA, XA, KrA, vhA)
; #define RW_STEP4(B) RW_STEP2(B); RW_STEP2((B) + 2)
; template <int DIR>
; DEVINL void rwkv_scan_dir(const Params& p, int task, int lane, int wave) {
;     ...
;     if (st > 0) { const int q0 = st - 16 + seg; yo[(long)(DIR ? (4095 - q0) : q0) * 1024] = f2bf(ykeep); }
;     RW_STEP(1, WvB, XB, KrB, vhB, WvA, XA, KrA, vhA);
;     RW_STEP2(2); RW_STEP4(4); RW_STEP4(8); RW_STEP4(12);
;     RW_STEP(16, WvA, XA, KrA, vhA, WvB, XB, KrB, vhB);
;     { const int q0 = st + seg; yo[(long)(DIR ? (4095 - q0) : q0) * 1024] = f2bf(ykeep); }
;     RW_STEP(17, WvB, XB, KrB, vhB, WvA, XA, KrA, vhA);
;     RW_STEP2(18); RW_STEP4(20); RW_STEP4(24); RW_STEP4(28);
;   }
;   {
;     const float ylast = allred16(ypart);
;     ykeep = (seg == 15) ? ylast : ykeep;
;     const int q0 = 4096 - 16 + seg; yo[(long)(DIR ? (4095 - q0) : q0) * 1024] = f2bf(ykeep);
	v_fma_mix_f32 v21, v10, v92, 0 op_sel:[0,0,0] op_sel_hi:[0,1,0]
	v_fma_mix_f32 v22, v12, v93, 0 op_sel:[0,0,0] op_sel_hi:[0,1,0]
	v_fma_mix_f32 v21, v11, v92, v21 op_sel:[0,1,0] op_sel_hi:[0,1,0]
	v_fma_mix_f32 v22, v13, v93, v22 op_sel:[0,1,0] op_sel_hi:[0,1,0]
	v_add_f32_e32 v63, v21, v22
	s_nop 1
	v_add_f32_dpp v48, v48, v48 row_ror:8 row_mask:0xf bank_mask:0x3
	v_add_f32_dpp v49, v49, v49 row_ror:8 row_mask:0xf bank_mask:0x3
	v_add_f32_dpp v50, v50, v50 row_ror:8 row_mask:0xf bank_mask:0x3
	v_add_f32_dpp v51, v51, v51 row_ror:8 row_mask:0xf bank_mask:0x3
	v_add_f32_dpp v52, v52, v52 row_ror:8 row_mask:0xf bank_mask:0x3
	v_add_f32_dpp v53, v53, v53 row_ror:8 row_mask:0xf bank_mask:0x3
	v_add_f32_dpp v54, v54, v54 row_ror:8 row_mask:0xf bank_mask:0x3
	v_add_f32_dpp v55, v55, v55 row_ror:8 row_mask:0xf bank_mask:0x3
	v_add_f32_dpp v48, v56, v56 row_ror:8 row_mask:0xf bank_mask:0xc
	v_add_f32_dpp v49, v57, v57 row_ror:8 row_mask:0xf bank_mask:0xc
	v_add_f32_dpp v50, v58, v58 row_ror:8 row_mask:0xf bank_mask:0xc
	v_add_f32_dpp v51, v59, v59 row_ror:8 row_mask:0xf bank_mask:0xc
	v_add_f32_dpp v52, v60, v60 row_ror:8 row_mask:0xf bank_mask:0xc
	v_add_f32_dpp v53, v61, v61 row_ror:8 row_mask:0xf bank_mask:0xc
	v_add_f32_dpp v54, v62, v62 row_ror:8 row_mask:0xf bank_mask:0xc
	v_add_f32_dpp v55, v63, v63 row_ror:8 row_mask:0xf bank_mask:0xc
	v_add_f32_dpp v48, v48, v48 row_ror:12 row_mask:0xf bank_mask:0x5
	v_add_f32_dpp v49, v49, v49 row_ror:12 row_mask:0xf bank_mask:0x5
	v_add_f32_dpp v50, v50, v50 row_ror:12 row_mask:0xf bank_mask:0x5
	v_add_f32_dpp v51, v51, v51 row_ror:12 row_mask:0xf bank_mask:0x5
	v_add_f32_dpp v48, v52, v52 row_ror:4 row_mask:0xf bank_mask:0xa
	v_add_f32_dpp v49, v53, v53 row_ror:4 row_mask:0xf bank_mask:0xa
	v_add_f32_dpp v50, v54, v54 row_ror:4 row_mask:0xf bank_mask:0xa
	v_add_f32_dpp v51, v55, v55 row_ror:4 row_mask:0xf bank_mask:0xa
	v_add_f32_dpp v64, v48, v48 quad_perm:[2,3,0,1] row_mask:0xf bank_mask:0xf bound_ctrl:1
	v_add_f32_dpp v65, v50, v50 quad_perm:[2,3,0,1] row_mask:0xf bank_mask:0xf bound_ctrl:1
	v_cndmask_b32_e64 v56, v64, v65, s[50:51]
	v_add_f32_dpp v64, v49, v49 quad_perm:[2,3,0,1] row_mask:0xf bank_mask:0xf bound_ctrl:1
	v_add_f32_dpp v65, v51, v51 quad_perm:[2,3,0,1] row_mask:0xf bank_mask:0xf bound_ctrl:1
	v_cndmask_b32_e64 v57, v64, v65, s[50:51]
	v_add_f32_dpp v64, v56, v56 quad_perm:[1,0,3,2] row_mask:0xf bank_mask:0xf bound_ctrl:1
	s_nop 0
	v_add_f32_dpp v65, v57, v57 quad_perm:[1,0,3,2] row_mask:0xf bank_mask:0xf bound_ctrl:1
	v_cndmask_b32_e64 v66, v64, v65, s[48:49]
	v_cvt_pk_bf16_f32 v66, v66, v66
	global_store_short v8, v66, s[12:13]
	s_sub_u32 s12, s12, 0x8000
	s_subb_u32 s13, s13, 0
